# modes 0/2: MFMA operands swapped (C^T accumulators), in-register relu2/bf16 pack -> bf16 LDS image -> 16B stores; next tile k-tiles 0/1 loaded during epilogue
# speedup vs baseline: 1.0835x; 1.0014x over previous
; #define G5_LOAD(k0)                                                                 \
;   {                                                                                 \
;     _Pragma("unroll") for (int i_ = 0; i_ < 4; ++i_) ra[i_] = ldg16(Ap + (size_t)(i_ * 64) * lda + (k0)); \
;     _Pragma("unroll") for (int i_ = 0; i_ < 4; ++i_) rb[i_] = ldg16(Bp + (size_t)(i_ * 64) * ldb + (k0)); \
;   }
; #define G5_STORE(s)                                                                 \
;   {                                                                                 \
;     _Pragma("unroll") for (int i_ = 0; i_ < 4; ++i_) *(u32x4*)(Sw + (s) * STG + i_ * 64 * GS) = ra[i_]; \
;     _Pragma("unroll") for (int i_ = 0; i_ < 4; ++i_) *(u32x4*)(Sw + (s) * STG + 256 * GS + i_ * 64 * GS) = rb[i_]; \
;   }
; template <typename Epi>
; DI void gemm_tile512(const u16* __restrict__ A, int lda, const u16* __restrict__ Bt, int ldb, int K, char* lds_all, Epi epi) {
;     ...
;   const int nk = K >> 6;
;   __syncthreads();
;   G5_LOAD(0);
;   G5_STORE(0);
;   G5_LOAD(64);
;   __syncthreads();
; DI void gemm_phase(const Params& p, int layer, int mode, int nrows, char* lds_all) {
;     ...
;   for (int i = jb;; i += nj) {
;     const int srl = i / per, rem = i - srl * per;
;     const int sr = xcd + nx * srl;
;     if (sr >= nsr) break;
;     const int tn = rem >> 1, tm = sr * 2 + (rem & 1);
;     const int m0 = tm * 256, n0 = tn * 256;
;     gemm_tile512(A + (size_t)m0 * lda, lda, Bt + (size_t)n0 * ldb, ldb, K, lds_all, [&](int half) {
.LBB0_198:
	s_mul_i32 s6, s4, 0xffffffea
	s_lshl_b32 s11, s5, 9
	s_lshl_b32 s5, s16, 8
	s_add_i32 s6, s6, s16
	s_and_b32 s5, s5, 0x100
	s_or_b32 s17, s5, s11
	s_lshl_b32 s5, s6, 7
	s_and_b32 s18, s5, 0xffffff00
	s_mul_i32 s6, s17, 0x900
	v_readlane_b32 s7, v250, 46
	s_mul_hi_i32 s5, s17, 0x900
	s_add_u32 s6, s7, s6
	v_readlane_b32 s7, v250, 47
	s_addc_u32 s7, s7, s5
	s_mul_i32 s8, s18, 0x900
	s_mul_hi_i32 s5, s18, 0x900
	s_add_u32 s8, s2, s8
	s_addc_u32 s9, s3, s5
	s_mov_b64 s[98:99], s[6:7]
	s_mov_b64 s[100:101], s[8:9]
	v_lshrrev_b32_e32 v239, 3, v165
	v_and_b32_e32 v0, 7, v165
	v_mul_u32_u24_e32 v206, 0x900, v239
	v_lshl_add_u32 v206, v0, 4, v206
	v_add_u32_e32 v207, 0x24000, v206
	v_add_u32_e32 v208, 0x48000, v206
	v_add_u32_e32 v238, 0x6c000, v206
	global_load_dwordx4 v[130:133], v206, s[98:99]
	global_load_dwordx4 v[134:137], v207, s[98:99]
	global_load_dwordx4 v[138:141], v208, s[98:99]
	global_load_dwordx4 v[142:145], v238, s[98:99]
	global_load_dwordx4 v[146:149], v206, s[100:101]
	global_load_dwordx4 v[150:153], v207, s[100:101]
	global_load_dwordx4 v[154:157], v208, s[100:101]
	global_load_dwordx4 v[158:161], v238, s[100:101]
	global_load_dwordx4 v[218:221], v206, s[98:99] offset:128
	global_load_dwordx4 v[222:225], v207, s[98:99] offset:128
	global_load_dwordx4 v[226:229], v208, s[98:99] offset:128
	global_load_dwordx4 v[230:233], v238, s[98:99] offset:128
	global_load_dwordx4 v[166:169], v206, s[100:101] offset:128
	global_load_dwordx4 v[170:173], v207, s[100:101] offset:128
	global_load_dwordx4 v[174:177], v208, s[100:101] offset:128
	global_load_dwordx4 v[190:193], v238, s[100:101] offset:128
	s_add_u32 s98, s98, 0x100
	s_addc_u32 s99, s99, 0
	s_add_u32 s100, s100, 0x100
	s_addc_u32 s101, s101, 0
	v_lshrrev_b32_e32 v239, 3, v165
	v_and_b32_e32 v0, 7, v165
	v_mul_u32_u24_e32 v180, 0x90, v239
	v_lshl_add_u32 v180, v0, 4, v180
	v_and_b32_e32 v239, 31, v165
	v_bfe_u32 v0, v165, 5, 1
	v_lshrrev_b32_e32 v179, 8, v165
	v_lshl_or_b32 v178, v179, 7, v239
	v_mul_u32_u24_e32 v178, 0x90, v178
	v_lshl_add_u32 v178, v0, 4, v178
	v_bfe_u32 v179, v165, 6, 2
	v_lshl_or_b32 v179, v179, 6, v239
	v_mul_u32_u24_e32 v179, 0x90, v179
	v_lshl_add_u32 v179, v0, 4, v179
	s_mov_b32 s12, 0x12000
	s_mov_b32 s13, 13
	s_barrier
	s_waitcnt vmcnt(15)
	ds_write_b128 v180, v[130:133]
	s_waitcnt vmcnt(14)
	ds_write_b128 v180, v[134:137] offset:9216
	s_waitcnt vmcnt(13)
	ds_write_b128 v180, v[138:141] offset:18432
	s_waitcnt vmcnt(12)
	ds_write_b128 v180, v[142:145] offset:27648
	s_waitcnt vmcnt(11)
	ds_write_b128 v180, v[146:149] offset:36864
	s_waitcnt vmcnt(10)
	ds_write_b128 v180, v[150:153] offset:46080
	s_waitcnt vmcnt(9)
	ds_write_b128 v180, v[154:157] offset:55296
	s_waitcnt vmcnt(8)
	ds_write_b128 v180, v[158:161] offset:64512
	v_add_u32_e32 v180, 0x12000, v180
	s_waitcnt vmcnt(7)
	ds_write_b128 v180, v[218:221]
	s_waitcnt vmcnt(6)
	ds_write_b128 v180, v[222:225] offset:9216
	s_waitcnt vmcnt(5)
	ds_write_b128 v180, v[226:229] offset:18432
	s_waitcnt vmcnt(4)
	ds_write_b128 v180, v[230:233] offset:27648
	s_waitcnt vmcnt(3)
	ds_write_b128 v180, v[166:169] offset:36864
	s_waitcnt vmcnt(2)
	ds_write_b128 v180, v[170:173] offset:46080
	s_waitcnt vmcnt(1)
	ds_write_b128 v180, v[174:177] offset:55296
	s_waitcnt vmcnt(0)
	ds_write_b128 v180, v[190:193] offset:64512
	s_waitcnt lgkmcnt(0)
	s_branch .Lg3_k_m0
.Lg3_start_m0:
	v_lshrrev_b32_e32 v239, 3, v165
	v_and_b32_e32 v0, 7, v165
	v_mul_u32_u24_e32 v180, 0x90, v239
	v_lshl_add_u32 v180, v0, 4, v180
	v_and_b32_e32 v239, 31, v165
	v_bfe_u32 v0, v165, 5, 1
	v_lshrrev_b32_e32 v179, 8, v165
	v_lshl_or_b32 v178, v179, 7, v239
	v_mul_u32_u24_e32 v178, 0x90, v178
	v_lshl_add_u32 v178, v0, 4, v178
	v_bfe_u32 v179, v165, 6, 2
	v_lshl_or_b32 v179, v179, 6, v239
	v_mul_u32_u24_e32 v179, 0x90, v179
	v_lshl_add_u32 v179, v0, 4, v179
	s_mov_b32 s12, 0x12000
	s_mov_b32 s13, 13
	s_barrier
	s_waitcnt vmcnt(31)
	ds_write_b128 v180, v[130:133]
	s_waitcnt vmcnt(30)
	ds_write_b128 v180, v[134:137] offset:9216
	s_waitcnt vmcnt(29)
	ds_write_b128 v180, v[138:141] offset:18432
	s_waitcnt vmcnt(28)
	ds_write_b128 v180, v[142:145] offset:27648
	s_waitcnt vmcnt(27)
	ds_write_b128 v180, v[146:149] offset:36864
	s_waitcnt vmcnt(26)
	ds_write_b128 v180, v[150:153] offset:46080
	s_waitcnt vmcnt(25)
	ds_write_b128 v180, v[154:157] offset:55296
	s_waitcnt vmcnt(24)
	ds_write_b128 v180, v[158:161] offset:64512
	v_add_u32_e32 v180, 0x12000, v180
	s_waitcnt vmcnt(23)
	ds_write_b128 v180, v[218:221]
	s_waitcnt vmcnt(22)
	ds_write_b128 v180, v[222:225] offset:9216
	s_waitcnt vmcnt(21)
	ds_write_b128 v180, v[226:229] offset:18432
	s_waitcnt vmcnt(20)
	ds_write_b128 v180, v[230:233] offset:27648
	s_waitcnt vmcnt(19)
	ds_write_b128 v180, v[166:169] offset:36864
	s_waitcnt vmcnt(18)
	ds_write_b128 v180, v[170:173] offset:46080
	s_waitcnt vmcnt(17)
	ds_write_b128 v180, v[174:177] offset:55296
	s_waitcnt vmcnt(16)
	ds_write_b128 v180, v[190:193] offset:64512
	s_waitcnt lgkmcnt(0)
; #define G5_LOAD(k0)                                                                 \
;   {                                                                                 \
;     _Pragma("unroll") for (int i_ = 0; i_ < 4; ++i_) ra[i_] = ldg16(Ap + (size_t)(i_ * 64) * lda + (k0)); \
;     _Pragma("unroll") for (int i_ = 0; i_ < 4; ++i_) rb[i_] = ldg16(Bp + (size_t)(i_ * 64) * ldb + (k0)); \
;   }
; #define G5_STORE(s)                                                                 \
;   {                                                                                 \
;     _Pragma("unroll") for (int i_ = 0; i_ < 4; ++i_) *(u32x4*)(Sw + (s) * STG + i_ * 64 * GS) = ra[i_]; \
;     _Pragma("unroll") for (int i_ = 0; i_ < 4; ++i_) *(u32x4*)(Sw + (s) * STG + 256 * GS + i_ * 64 * GS) = rb[i_]; \
;   }
; template <typename Epi>
; DI void gemm_tile512(const u16* __restrict__ A, int lda, const u16* __restrict__ Bt, int ldb, int K, char* lds_all, Epi epi) {
;     ...
;   for (int kt = 0; kt + 2 < nk; ++kt) {
;     const int cur = kt & 1;
;     G5_COMPUTE(cur);
;     G5_STORE(cur ^ 1);
;     G5_LOAD((kt + 2) << 6);
;     __syncthreads();
;   }
.Lg3_k_m0:
	s_barrier
	ds_read_b128 v[194:197], v179 offset:36864
	ds_read_b128 v[166:169], v178
	ds_read_b128 v[198:201], v179 offset:41472
	ds_read_b128 v[170:173], v178 offset:4608
	ds_read_b128 v[174:177], v178 offset:9216
	ds_read_b128 v[190:193], v178 offset:13824
	s_waitcnt lgkmcnt(4)
	v_mfma_f32_32x32x16_bf16 v[114:129], v[194:197], v[166:169], 0
	ds_read_b128 v[234:237], v179 offset:36896
	s_waitcnt lgkmcnt(4)
	v_mfma_f32_32x32x16_bf16 v[98:113], v[198:201], v[166:169], 0
	ds_read_b128 v[218:221], v178 offset:32
	global_load_dwordx4 v[130:133], v206, s[98:99]
	s_waitcnt lgkmcnt(4)
	v_mfma_f32_32x32x16_bf16 v[82:97], v[194:197], v[170:173], 0
	ds_read_b128 v[202:205], v179 offset:41504
	v_mfma_f32_32x32x16_bf16 v[66:81], v[198:201], v[170:173], 0
	ds_read_b128 v[222:225], v178 offset:4640
	global_load_dwordx4 v[134:137], v207, s[98:99]
	s_waitcnt lgkmcnt(5)
	v_mfma_f32_32x32x16_bf16 v[50:65], v[194:197], v[174:177], 0
	ds_read_b128 v[226:229], v178 offset:9248
	v_mfma_f32_32x32x16_bf16 v[34:49], v[198:201], v[174:177], 0
	ds_read_b128 v[230:233], v178 offset:13856
	global_load_dwordx4 v[138:141], v208, s[98:99]
	s_waitcnt lgkmcnt(6)
	v_mfma_f32_32x32x16_bf16 v[18:33], v[194:197], v[190:193], 0
	v_mfma_f32_32x32x16_bf16 v[2:17], v[198:201], v[190:193], 0
	global_load_dwordx4 v[142:145], v238, s[98:99]
	s_waitcnt lgkmcnt(4)
	v_mfma_f32_32x32x16_bf16 v[114:129], v[234:237], v[218:221], v[114:129]
	ds_read_b128 v[194:197], v179 offset:36928
	s_waitcnt lgkmcnt(4)
	v_mfma_f32_32x32x16_bf16 v[98:113], v[202:205], v[218:221], v[98:113]
	ds_read_b128 v[166:169], v178 offset:64
	global_load_dwordx4 v[146:149], v206, s[100:101]
	s_waitcnt lgkmcnt(4)
	v_mfma_f32_32x32x16_bf16 v[82:97], v[234:237], v[222:225], v[82:97]
	ds_read_b128 v[198:201], v179 offset:41536
	v_mfma_f32_32x32x16_bf16 v[66:81], v[202:205], v[222:225], v[66:81]
	ds_read_b128 v[170:173], v178 offset:4672
	global_load_dwordx4 v[150:153], v207, s[100:101]
	s_waitcnt lgkmcnt(5)
	v_mfma_f32_32x32x16_bf16 v[50:65], v[234:237], v[226:229], v[50:65]
	ds_read_b128 v[174:177], v178 offset:9280
	v_mfma_f32_32x32x16_bf16 v[34:49], v[202:205], v[226:229], v[34:49]
	ds_read_b128 v[190:193], v178 offset:13888
	global_load_dwordx4 v[154:157], v208, s[100:101]
	s_waitcnt lgkmcnt(6)
	v_mfma_f32_32x32x16_bf16 v[18:33], v[234:237], v[230:233], v[18:33]
	v_mfma_f32_32x32x16_bf16 v[2:17], v[202:205], v[230:233], v[2:17]
	global_load_dwordx4 v[158:161], v238, s[100:101]
	v_subrev_u32_e32 v180, s12, v180
	s_waitcnt lgkmcnt(4)
	v_mfma_f32_32x32x16_bf16 v[114:129], v[194:197], v[166:169], v[114:129]
	ds_read_b128 v[234:237], v179 offset:36960
	s_waitcnt lgkmcnt(4)
	v_mfma_f32_32x32x16_bf16 v[98:113], v[198:201], v[166:169], v[98:113]
	ds_read_b128 v[218:221], v178 offset:96
	s_waitcnt lgkmcnt(4)
	v_mfma_f32_32x32x16_bf16 v[82:97], v[194:197], v[170:173], v[82:97]
	ds_read_b128 v[202:205], v179 offset:41568
	v_mfma_f32_32x32x16_bf16 v[66:81], v[198:201], v[170:173], v[66:81]
	ds_read_b128 v[222:225], v178 offset:4704
	s_waitcnt lgkmcnt(5)
	v_mfma_f32_32x32x16_bf16 v[50:65], v[194:197], v[174:177], v[50:65]
	ds_read_b128 v[226:229], v178 offset:9312
	v_mfma_f32_32x32x16_bf16 v[34:49], v[198:201], v[174:177], v[34:49]
	ds_read_b128 v[230:233], v178 offset:13920
	v_add_u32_e32 v178, s12, v178
	v_add_u32_e32 v179, s12, v179
	s_waitcnt lgkmcnt(6)
	v_mfma_f32_32x32x16_bf16 v[18:33], v[194:197], v[190:193], v[18:33]
	v_mfma_f32_32x32x16_bf16 v[2:17], v[198:201], v[190:193], v[2:17]
	s_sub_u32 s12, 0, s12
	s_add_u32 s98, s98, 0x80
	s_addc_u32 s99, s99, 0
	s_add_u32 s100, s100, 0x80
	s_addc_u32 s101, s101, 0
	s_waitcnt lgkmcnt(0)
.Lg3_loop_m0:
	s_barrier
	ds_read_b128 v[194:197], v179 offset:36864
	ds_read_b128 v[166:169], v178
	v_mfma_f32_32x32x16_bf16 v[114:129], v[234:237], v[218:221], v[114:129]
	ds_read_b128 v[198:201], v179 offset:41472
	v_mfma_f32_32x32x16_bf16 v[98:113], v[202:205], v[218:221], v[98:113]
	ds_read_b128 v[170:173], v178 offset:4608
	v_mfma_f32_32x32x16_bf16 v[82:97], v[234:237], v[222:225], v[82:97]
	ds_read_b128 v[174:177], v178 offset:9216
	v_mfma_f32_32x32x16_bf16 v[66:81], v[202:205], v[222:225], v[66:81]
	ds_read_b128 v[190:193], v178 offset:13824
	v_mfma_f32_32x32x16_bf16 v[50:65], v[234:237], v[226:229], v[50:65]
	v_mfma_f32_32x32x16_bf16 v[34:49], v[202:205], v[226:229], v[34:49]
	v_mfma_f32_32x32x16_bf16 v[18:33], v[234:237], v[230:233], v[18:33]
	v_mfma_f32_32x32x16_bf16 v[2:17], v[202:205], v[230:233], v[2:17]
	s_waitcnt lgkmcnt(4)
	v_mfma_f32_32x32x16_bf16 v[114:129], v[194:197], v[166:169], v[114:129]
	ds_read_b128 v[234:237], v179 offset:36896
	s_waitcnt lgkmcnt(4)
	v_mfma_f32_32x32x16_bf16 v[98:113], v[198:201], v[166:169], v[98:113]
	ds_read_b128 v[218:221], v178 offset:32
	s_waitcnt vmcnt(7)
	ds_write_b128 v180, v[130:133]
	global_load_dwordx4 v[130:133], v206, s[98:99]
	s_waitcnt lgkmcnt(5)
	v_mfma_f32_32x32x16_bf16 v[82:97], v[194:197], v[170:173], v[82:97]
	ds_read_b128 v[202:205], v179 offset:41504
	v_mfma_f32_32x32x16_bf16 v[66:81], v[198:201], v[170:173], v[66:81]
	ds_read_b128 v[222:225], v178 offset:4640
	s_waitcnt vmcnt(7)
	ds_write_b128 v180, v[134:137] offset:9216
	global_load_dwordx4 v[134:137], v207, s[98:99]
	s_waitcnt lgkmcnt(7)
	v_mfma_f32_32x32x16_bf16 v[50:65], v[194:197], v[174:177], v[50:65]
	ds_read_b128 v[226:229], v178 offset:9248
	v_mfma_f32_32x32x16_bf16 v[34:49], v[198:201], v[174:177], v[34:49]
	ds_read_b128 v[230:233], v178 offset:13856
	s_waitcnt vmcnt(7)
	ds_write_b128 v180, v[138:141] offset:18432
	global_load_dwordx4 v[138:141], v208, s[98:99]
	s_waitcnt lgkmcnt(9)
; #define G5_LOAD(k0)                                                                 \
;   {                                                                                 \
;     _Pragma("unroll") for (int i_ = 0; i_ < 4; ++i_) ra[i_] = ldg16(Ap + (size_t)(i_ * 64) * lda + (k0)); \
;     _Pragma("unroll") for (int i_ = 0; i_ < 4; ++i_) rb[i_] = ldg16(Bp + (size_t)(i_ * 64) * ldb + (k0)); \
;   }
; #define G5_STORE(s)                                                                 \
;   {                                                                                 \
;     _Pragma("unroll") for (int i_ = 0; i_ < 4; ++i_) *(u32x4*)(Sw + (s) * STG + i_ * 64 * GS) = ra[i_]; \
;     _Pragma("unroll") for (int i_ = 0; i_ < 4; ++i_) *(u32x4*)(Sw + (s) * STG + 256 * GS + i_ * 64 * GS) = rb[i_]; \
;   }
; template <typename Epi>
; DI void gemm_tile512(const u16* __restrict__ A, int lda, const u16* __restrict__ Bt, int ldb, int K, char* lds_all, Epi epi) {
;     ...
;   for (int kt = 0; kt + 2 < nk; ++kt) {
;     const int cur = kt & 1;
;     G5_COMPUTE(cur);
;     G5_STORE(cur ^ 1);
;     G5_LOAD((kt + 2) << 6);
;     __syncthreads();
;   }
;   {
;     const int cur = (nk - 2) & 1;
;     G5_COMPUTE(cur);
;     G5_STORE(cur ^ 1);
;     __syncthreads();
;     G5_COMPUTE(cur ^ 1);
;   }
	v_mfma_f32_32x32x16_bf16 v[18:33], v[194:197], v[190:193], v[18:33]
	v_mfma_f32_32x32x16_bf16 v[2:17], v[198:201], v[190:193], v[2:17]
	s_waitcnt vmcnt(7)
	ds_write_b128 v180, v[142:145] offset:27648
	global_load_dwordx4 v[142:145], v238, s[98:99]
	s_waitcnt lgkmcnt(8)
	v_mfma_f32_32x32x16_bf16 v[114:129], v[234:237], v[218:221], v[114:129]
	ds_read_b128 v[194:197], v179 offset:36928
	s_waitcnt lgkmcnt(7)
	v_mfma_f32_32x32x16_bf16 v[98:113], v[202:205], v[218:221], v[98:113]
	ds_read_b128 v[166:169], v178 offset:64
	s_waitcnt vmcnt(7)
	ds_write_b128 v180, v[146:149] offset:36864
	global_load_dwordx4 v[146:149], v206, s[100:101]
	s_waitcnt lgkmcnt(8)
	v_mfma_f32_32x32x16_bf16 v[82:97], v[234:237], v[222:225], v[82:97]
	ds_read_b128 v[198:201], v179 offset:41536
	v_mfma_f32_32x32x16_bf16 v[66:81], v[202:205], v[222:225], v[66:81]
	ds_read_b128 v[170:173], v178 offset:4672
	s_waitcnt vmcnt(7)
	ds_write_b128 v180, v[150:153] offset:46080
	global_load_dwordx4 v[150:153], v207, s[100:101]
	s_waitcnt lgkmcnt(9)
	v_mfma_f32_32x32x16_bf16 v[50:65], v[234:237], v[226:229], v[50:65]
	ds_read_b128 v[174:177], v178 offset:9280
	v_mfma_f32_32x32x16_bf16 v[34:49], v[202:205], v[226:229], v[34:49]
	ds_read_b128 v[190:193], v178 offset:13888
	s_waitcnt vmcnt(7)
	ds_write_b128 v180, v[154:157] offset:55296
	global_load_dwordx4 v[154:157], v208, s[100:101]
	s_waitcnt lgkmcnt(11)
	v_mfma_f32_32x32x16_bf16 v[18:33], v[234:237], v[230:233], v[18:33]
	v_mfma_f32_32x32x16_bf16 v[2:17], v[202:205], v[230:233], v[2:17]
	s_waitcnt vmcnt(7)
	ds_write_b128 v180, v[158:161] offset:64512
	global_load_dwordx4 v[158:161], v238, s[100:101]
	v_subrev_u32_e32 v180, s12, v180
	s_waitcnt lgkmcnt(8)
	v_mfma_f32_32x32x16_bf16 v[114:129], v[194:197], v[166:169], v[114:129]
	ds_read_b128 v[234:237], v179 offset:36960
	s_waitcnt lgkmcnt(7)
	v_mfma_f32_32x32x16_bf16 v[98:113], v[198:201], v[166:169], v[98:113]
	ds_read_b128 v[218:221], v178 offset:96
	s_waitcnt lgkmcnt(7)
	v_mfma_f32_32x32x16_bf16 v[82:97], v[194:197], v[170:173], v[82:97]
	ds_read_b128 v[202:205], v179 offset:41568
	v_mfma_f32_32x32x16_bf16 v[66:81], v[198:201], v[170:173], v[66:81]
	ds_read_b128 v[222:225], v178 offset:4704
	s_waitcnt lgkmcnt(7)
	v_mfma_f32_32x32x16_bf16 v[50:65], v[194:197], v[174:177], v[50:65]
	ds_read_b128 v[226:229], v178 offset:9312
	v_mfma_f32_32x32x16_bf16 v[34:49], v[198:201], v[174:177], v[34:49]
	ds_read_b128 v[230:233], v178 offset:13920
	v_add_u32_e32 v178, s12, v178
	v_add_u32_e32 v179, s12, v179
	s_waitcnt lgkmcnt(8)
	v_mfma_f32_32x32x16_bf16 v[18:33], v[194:197], v[190:193], v[18:33]
	v_mfma_f32_32x32x16_bf16 v[2:17], v[198:201], v[190:193], v[2:17]
	s_sub_u32 s12, 0, s12
	s_add_u32 s98, s98, 0x80
	s_addc_u32 s99, s99, 0
	s_add_u32 s100, s100, 0x80
	s_addc_u32 s101, s101, 0
	s_waitcnt lgkmcnt(0)
	s_sub_u32 s13, s13, 1
	s_cmp_lg_u32 s13, 0
	s_cbranch_scc1 .Lg3_loop_m0
	s_barrier
	ds_read_b128 v[194:197], v179 offset:36864
	ds_read_b128 v[166:169], v178
	v_mfma_f32_32x32x16_bf16 v[114:129], v[234:237], v[218:221], v[114:129]
	ds_read_b128 v[198:201], v179 offset:41472
	v_mfma_f32_32x32x16_bf16 v[98:113], v[202:205], v[218:221], v[98:113]
	ds_read_b128 v[170:173], v178 offset:4608
	v_mfma_f32_32x32x16_bf16 v[82:97], v[234:237], v[222:225], v[82:97]
	ds_read_b128 v[174:177], v178 offset:9216
	v_mfma_f32_32x32x16_bf16 v[66:81], v[202:205], v[222:225], v[66:81]
	ds_read_b128 v[190:193], v178 offset:13824
	v_mfma_f32_32x32x16_bf16 v[50:65], v[234:237], v[226:229], v[50:65]
	v_mfma_f32_32x32x16_bf16 v[34:49], v[202:205], v[226:229], v[34:49]
	v_mfma_f32_32x32x16_bf16 v[18:33], v[234:237], v[230:233], v[18:33]
	v_mfma_f32_32x32x16_bf16 v[2:17], v[202:205], v[230:233], v[2:17]
	s_waitcnt lgkmcnt(4)
	v_mfma_f32_32x32x16_bf16 v[114:129], v[194:197], v[166:169], v[114:129]
	ds_read_b128 v[234:237], v179 offset:36896
	s_waitcnt lgkmcnt(4)
	v_mfma_f32_32x32x16_bf16 v[98:113], v[198:201], v[166:169], v[98:113]
	ds_read_b128 v[218:221], v178 offset:32
	s_waitcnt vmcnt(7)
	ds_write_b128 v180, v[130:133]
	s_waitcnt lgkmcnt(5)
	v_mfma_f32_32x32x16_bf16 v[82:97], v[194:197], v[170:173], v[82:97]
	ds_read_b128 v[202:205], v179 offset:41504
	v_mfma_f32_32x32x16_bf16 v[66:81], v[198:201], v[170:173], v[66:81]
	ds_read_b128 v[222:225], v178 offset:4640
	s_waitcnt vmcnt(6)
	ds_write_b128 v180, v[134:137] offset:9216
	s_waitcnt lgkmcnt(7)
	v_mfma_f32_32x32x16_bf16 v[50:65], v[194:197], v[174:177], v[50:65]
	ds_read_b128 v[226:229], v178 offset:9248
	v_mfma_f32_32x32x16_bf16 v[34:49], v[198:201], v[174:177], v[34:49]
	ds_read_b128 v[230:233], v178 offset:13856
	s_waitcnt vmcnt(5)
	ds_write_b128 v180, v[138:141] offset:18432
	s_waitcnt lgkmcnt(9)
	v_mfma_f32_32x32x16_bf16 v[18:33], v[194:197], v[190:193], v[18:33]
	v_mfma_f32_32x32x16_bf16 v[2:17], v[198:201], v[190:193], v[2:17]
	s_waitcnt vmcnt(4)
	ds_write_b128 v180, v[142:145] offset:27648
	s_waitcnt lgkmcnt(8)
	v_mfma_f32_32x32x16_bf16 v[114:129], v[234:237], v[218:221], v[114:129]
	ds_read_b128 v[194:197], v179 offset:36928
	s_waitcnt lgkmcnt(7)
	v_mfma_f32_32x32x16_bf16 v[98:113], v[202:205], v[218:221], v[98:113]
	ds_read_b128 v[166:169], v178 offset:64
	s_waitcnt vmcnt(3)
	ds_write_b128 v180, v[146:149] offset:36864
	s_waitcnt lgkmcnt(8)
	v_mfma_f32_32x32x16_bf16 v[82:97], v[234:237], v[222:225], v[82:97]
	ds_read_b128 v[198:201], v179 offset:41536
	v_mfma_f32_32x32x16_bf16 v[66:81], v[202:205], v[222:225], v[66:81]
	ds_read_b128 v[170:173], v178 offset:4672
	s_waitcnt vmcnt(2)
	ds_write_b128 v180, v[150:153] offset:46080
	s_waitcnt lgkmcnt(9)
; #define G5_STORE(s)                                                                 \
;   {                                                                                 \
;     _Pragma("unroll") for (int i_ = 0; i_ < 4; ++i_) *(u32x4*)(Sw + (s) * STG + i_ * 64 * GS) = ra[i_]; \
;     _Pragma("unroll") for (int i_ = 0; i_ < 4; ++i_) *(u32x4*)(Sw + (s) * STG + 256 * GS + i_ * 64 * GS) = rb[i_]; \
;   }
; template <typename Epi>
; DI void gemm_tile512(const u16* __restrict__ A, int lda, const u16* __restrict__ Bt, int ldb, int K, char* lds_all, Epi epi) {
;     ...
;   {
;     const int cur = (nk - 2) & 1;
;     G5_COMPUTE(cur);
;     G5_STORE(cur ^ 1);
;     __syncthreads();
;     G5_COMPUTE(cur ^ 1);
;   }
; DI void gemm_phase(const Params& p, int layer, int mode, int nrows, char* lds_all) {
;     ...
;             if (n0 == C_BAB && c8 < 16) {
;               *(float4*)((float*)(p.ws + O_GRAW) + (size_t)row * 16 + c8) = v0;
;               *(float4*)((float*)(p.ws + O_GRAW) + (size_t)row * 16 + c8 + 4) = v1;
;             }
	v_mfma_f32_32x32x16_bf16 v[50:65], v[234:237], v[226:229], v[50:65]
	ds_read_b128 v[174:177], v178 offset:9280
	v_mfma_f32_32x32x16_bf16 v[34:49], v[202:205], v[226:229], v[34:49]
	ds_read_b128 v[190:193], v178 offset:13888
	s_waitcnt vmcnt(1)
	ds_write_b128 v180, v[154:157] offset:55296
	s_waitcnt lgkmcnt(11)
	v_mfma_f32_32x32x16_bf16 v[18:33], v[234:237], v[230:233], v[18:33]
	v_mfma_f32_32x32x16_bf16 v[2:17], v[202:205], v[230:233], v[2:17]
	s_waitcnt vmcnt(0)
	ds_write_b128 v180, v[158:161] offset:64512
	v_subrev_u32_e32 v180, s12, v180
	s_waitcnt lgkmcnt(8)
	v_mfma_f32_32x32x16_bf16 v[114:129], v[194:197], v[166:169], v[114:129]
	ds_read_b128 v[234:237], v179 offset:36960
	s_waitcnt lgkmcnt(7)
	v_mfma_f32_32x32x16_bf16 v[98:113], v[198:201], v[166:169], v[98:113]
	ds_read_b128 v[218:221], v178 offset:96
	s_waitcnt lgkmcnt(7)
	v_mfma_f32_32x32x16_bf16 v[82:97], v[194:197], v[170:173], v[82:97]
	ds_read_b128 v[202:205], v179 offset:41568
	v_mfma_f32_32x32x16_bf16 v[66:81], v[198:201], v[170:173], v[66:81]
	ds_read_b128 v[222:225], v178 offset:4704
	s_waitcnt lgkmcnt(7)
	v_mfma_f32_32x32x16_bf16 v[50:65], v[194:197], v[174:177], v[50:65]
	ds_read_b128 v[226:229], v178 offset:9312
	v_mfma_f32_32x32x16_bf16 v[34:49], v[198:201], v[174:177], v[34:49]
	ds_read_b128 v[230:233], v178 offset:13920
	v_add_u32_e32 v178, s12, v178
	v_add_u32_e32 v179, s12, v179
	s_waitcnt lgkmcnt(8)
	v_mfma_f32_32x32x16_bf16 v[18:33], v[194:197], v[190:193], v[18:33]
	v_mfma_f32_32x32x16_bf16 v[2:17], v[198:201], v[190:193], v[2:17]
	s_sub_u32 s12, 0, s12
	s_add_u32 s98, s98, 0x80
	s_addc_u32 s99, s99, 0
	s_add_u32 s100, s100, 0x80
	s_addc_u32 s101, s101, 0
	s_waitcnt lgkmcnt(0)
	s_barrier
	ds_read_b128 v[194:197], v179 offset:36864
	ds_read_b128 v[166:169], v178
	v_mfma_f32_32x32x16_bf16 v[114:129], v[234:237], v[218:221], v[114:129]
	ds_read_b128 v[198:201], v179 offset:41472
	v_mfma_f32_32x32x16_bf16 v[98:113], v[202:205], v[218:221], v[98:113]
	ds_read_b128 v[170:173], v178 offset:4608
	v_mfma_f32_32x32x16_bf16 v[82:97], v[234:237], v[222:225], v[82:97]
	ds_read_b128 v[174:177], v178 offset:9216
	v_mfma_f32_32x32x16_bf16 v[66:81], v[202:205], v[222:225], v[66:81]
	ds_read_b128 v[190:193], v178 offset:13824
	v_mfma_f32_32x32x16_bf16 v[50:65], v[234:237], v[226:229], v[50:65]
	v_mfma_f32_32x32x16_bf16 v[34:49], v[202:205], v[226:229], v[34:49]
	v_mfma_f32_32x32x16_bf16 v[18:33], v[234:237], v[230:233], v[18:33]
	v_mfma_f32_32x32x16_bf16 v[2:17], v[202:205], v[230:233], v[2:17]
	s_waitcnt lgkmcnt(4)
	v_mfma_f32_32x32x16_bf16 v[114:129], v[194:197], v[166:169], v[114:129]
	ds_read_b128 v[234:237], v179 offset:36896
	s_waitcnt lgkmcnt(4)
	v_mfma_f32_32x32x16_bf16 v[98:113], v[198:201], v[166:169], v[98:113]
	ds_read_b128 v[218:221], v178 offset:32
	s_waitcnt lgkmcnt(4)
	v_mfma_f32_32x32x16_bf16 v[82:97], v[194:197], v[170:173], v[82:97]
	ds_read_b128 v[202:205], v179 offset:41504
	v_mfma_f32_32x32x16_bf16 v[66:81], v[198:201], v[170:173], v[66:81]
	ds_read_b128 v[222:225], v178 offset:4640
	s_waitcnt lgkmcnt(5)
	v_mfma_f32_32x32x16_bf16 v[50:65], v[194:197], v[174:177], v[50:65]
	ds_read_b128 v[226:229], v178 offset:9248
	v_mfma_f32_32x32x16_bf16 v[34:49], v[198:201], v[174:177], v[34:49]
	ds_read_b128 v[230:233], v178 offset:13856
	s_waitcnt lgkmcnt(6)
	v_mfma_f32_32x32x16_bf16 v[18:33], v[194:197], v[190:193], v[18:33]
	v_mfma_f32_32x32x16_bf16 v[2:17], v[198:201], v[190:193], v[2:17]
	s_waitcnt lgkmcnt(4)
	v_mfma_f32_32x32x16_bf16 v[114:129], v[234:237], v[218:221], v[114:129]
	ds_read_b128 v[194:197], v179 offset:36928
	s_waitcnt lgkmcnt(4)
	v_mfma_f32_32x32x16_bf16 v[98:113], v[202:205], v[218:221], v[98:113]
	ds_read_b128 v[166:169], v178 offset:64
	s_waitcnt lgkmcnt(4)
	v_mfma_f32_32x32x16_bf16 v[82:97], v[234:237], v[222:225], v[82:97]
	ds_read_b128 v[198:201], v179 offset:41536
	v_mfma_f32_32x32x16_bf16 v[66:81], v[202:205], v[222:225], v[66:81]
	ds_read_b128 v[170:173], v178 offset:4672
	s_waitcnt lgkmcnt(5)
	v_mfma_f32_32x32x16_bf16 v[50:65], v[234:237], v[226:229], v[50:65]
	ds_read_b128 v[174:177], v178 offset:9280
	v_mfma_f32_32x32x16_bf16 v[34:49], v[202:205], v[226:229], v[34:49]
	ds_read_b128 v[190:193], v178 offset:13888
	s_waitcnt lgkmcnt(6)
	v_mfma_f32_32x32x16_bf16 v[18:33], v[234:237], v[230:233], v[18:33]
	v_mfma_f32_32x32x16_bf16 v[2:17], v[202:205], v[230:233], v[2:17]
	s_waitcnt lgkmcnt(4)
	v_mfma_f32_32x32x16_bf16 v[114:129], v[194:197], v[166:169], v[114:129]
	ds_read_b128 v[234:237], v179 offset:36960
	s_waitcnt lgkmcnt(4)
	v_mfma_f32_32x32x16_bf16 v[98:113], v[198:201], v[166:169], v[98:113]
	ds_read_b128 v[218:221], v178 offset:96
	s_waitcnt lgkmcnt(4)
	v_mfma_f32_32x32x16_bf16 v[82:97], v[194:197], v[170:173], v[82:97]
	ds_read_b128 v[202:205], v179 offset:41568
	v_mfma_f32_32x32x16_bf16 v[66:81], v[198:201], v[170:173], v[66:81]
	ds_read_b128 v[222:225], v178 offset:4704
	s_waitcnt lgkmcnt(5)
	v_mfma_f32_32x32x16_bf16 v[50:65], v[194:197], v[174:177], v[50:65]
	ds_read_b128 v[226:229], v178 offset:9312
	v_mfma_f32_32x32x16_bf16 v[34:49], v[198:201], v[174:177], v[34:49]
	ds_read_b128 v[230:233], v178 offset:13920
	s_waitcnt lgkmcnt(6)
	v_mfma_f32_32x32x16_bf16 v[18:33], v[194:197], v[190:193], v[18:33]
	v_mfma_f32_32x32x16_bf16 v[2:17], v[198:201], v[190:193], v[2:17]
	s_waitcnt lgkmcnt(0)
	v_mfma_f32_32x32x16_bf16 v[114:129], v[234:237], v[218:221], v[114:129]
	v_mfma_f32_32x32x16_bf16 v[98:113], v[202:205], v[218:221], v[98:113]
	v_mfma_f32_32x32x16_bf16 v[82:97], v[234:237], v[222:225], v[82:97]
	v_mfma_f32_32x32x16_bf16 v[66:81], v[202:205], v[222:225], v[66:81]
	v_mfma_f32_32x32x16_bf16 v[50:65], v[234:237], v[226:229], v[50:65]
	v_mfma_f32_32x32x16_bf16 v[34:49], v[202:205], v[226:229], v[34:49]
	v_mfma_f32_32x32x16_bf16 v[18:33], v[234:237], v[230:233], v[18:33]
	v_mfma_f32_32x32x16_bf16 v[2:17], v[202:205], v[230:233], v[2:17]
	s_cmpk_lg_i32 s18, 0x600
	s_cbranch_scc1 .Lepi0_nograw
	v_bfe_u32 v195, v165, 6, 2
	v_cmp_eq_u32_e32 vcc, 0, v195
	s_and_saveexec_b64 s[8:9], vcc
	s_cbranch_execz .Lepi0_graw_done
	v_lshrrev_b32_e32 v195, 8, v165
	v_and_b32_e32 v196, 31, v165
	v_lshl_or_b32 v195, v195, 7, v196
	v_lshlrev_b32_e32 v195, 6, v195
	v_bfe_u32 v196, v165, 5, 1
	v_lshl_or_b32 v195, v196, 4, v195
	v_readlane_b32 s22, v250, 52
	v_readlane_b32 s23, v250, 53
	s_lshl_b32 s20, s17, 6
	s_add_u32 s22, s22, s20
	s_addc_u32 s23, s23, 0
	global_store_dwordx4 v195, v[114:117], s[22:23]
	global_store_dwordx4 v195, v[118:121], s[22:23] offset:32
	global_store_dwordx4 v195, v[82:85], s[22:23] offset:2048
	global_store_dwordx4 v195, v[86:89], s[22:23] offset:2080
	s_add_u32 s22, s22, 0x1000
	s_addc_u32 s23, s23, 0
	global_store_dwordx4 v195, v[50:53], s[22:23]
	global_store_dwordx4 v195, v[54:57], s[22:23] offset:32
	global_store_dwordx4 v195, v[18:21], s[22:23] offset:2048
	global_store_dwordx4 v195, v[22:25], s[22:23] offset:2080

; DI void gemm_phase(const Params& p, int layer, int mode, int nrows, char* lds_all) {
;     ...
;   for (int i = jb;; i += nj) {
;     const int srl = i / per, rem = i - srl * per;
;     const int sr = xcd + nx * srl;
;     if (sr >= nsr) break;
;     const int tn = rem >> 1, tm = sr * 2 + (rem & 1);
;     ...
;           const float4 v0 = *(const float4*)(Cs + rr * CSW + c8), v1 = *(const float4*)(Cs + rr * CSW + c8 + 4);
;           if (mode == 0) {
;             uint4 o;
;             o.x = pack2(v0.x, v0.y); o.y = pack2(v0.z, v0.w); o.z = pack2(v1.x, v1.y); o.w = pack2(v1.z, v1.w);
;             *(uint4*)((u16*)(p.ws + O_Z) + (size_t)row * ZW + col) = o;
.Lepi0_nograw:
	s_mul_i32 s10, s17, 0x1600
	s_lshl_b32 s20, s18, 1
	s_add_u32 s10, s10, s20
	v_lshrrev_b32_e32 v237, 5, v165
	v_and_b32_e32 v194, 31, v165
	v_mul_u32_u24_e32 v234, 0x1600, v237
	v_lshl_add_u32 v234, v194, 4, v234
	v_add_u32_e32 v234, s10, v234
	v_readlane_b32 s4, v251, 9
	s_add_i32 s16, s16, s4
	s_mul_hi_i32 s4, s16, 0x2e8ba2e9
	s_lshr_b32 s5, s4, 31
	s_ashr_i32 s4, s4, 2
	s_add_i32 s4, s4, s5
	v_readlane_b32 s5, v252, 2
	v_readlane_b32 s6, v252, 6
	s_lshl_b32 s5, s4, s5
	s_add_i32 s15, s15, s6
	v_readlane_b32 s6, v252, 9
	s_add_i32 s5, s5, s19
	s_add_i32 s14, s14, s6
	s_cmpk_lt_i32 s5, 0x88
	s_cselect_b32 s10, 1, 0
	s_cmp_eq_u32 s10, 0
	s_cbranch_scc1 .Lg3_nonext_m0
	s_mul_i32 s6, s4, 0xffffffea
	s_lshl_b32 s11, s5, 9
	s_lshl_b32 s5, s16, 8
	s_add_i32 s6, s6, s16
	s_and_b32 s5, s5, 0x100
	s_or_b32 s17, s5, s11
	s_lshl_b32 s5, s6, 7
	s_and_b32 s18, s5, 0xffffff00
	s_mul_i32 s6, s17, 0x900
	v_readlane_b32 s7, v250, 46
	s_mul_hi_i32 s5, s17, 0x900
	s_add_u32 s6, s7, s6
	v_readlane_b32 s7, v250, 47
	s_addc_u32 s7, s7, s5
	s_mul_i32 s8, s18, 0x900
	s_mul_hi_i32 s5, s18, 0x900
	s_add_u32 s8, s2, s8
	s_addc_u32 s9, s3, s5
	s_mov_b64 s[98:99], s[6:7]
	s_mov_b64 s[100:101], s[8:9]
	v_lshrrev_b32_e32 v239, 3, v165
	v_and_b32_e32 v0, 7, v165
	v_mul_u32_u24_e32 v206, 0x900, v239
	v_lshl_add_u32 v206, v0, 4, v206
	v_add_u32_e32 v207, 0x24000, v206
	v_add_u32_e32 v208, 0x48000, v206
	v_add_u32_e32 v238, 0x6c000, v206
	global_load_dwordx4 v[130:133], v206, s[98:99]
	global_load_dwordx4 v[134:137], v207, s[98:99]
	global_load_dwordx4 v[138:141], v208, s[98:99]
	global_load_dwordx4 v[142:145], v238, s[98:99]
	global_load_dwordx4 v[146:149], v206, s[100:101]
	global_load_dwordx4 v[150:153], v207, s[100:101]
	global_load_dwordx4 v[154:157], v208, s[100:101]
	global_load_dwordx4 v[158:161], v238, s[100:101]
	global_load_dwordx4 v[218:221], v206, s[98:99] offset:128
	global_load_dwordx4 v[222:225], v207, s[98:99] offset:128
	global_load_dwordx4 v[226:229], v208, s[98:99] offset:128
	global_load_dwordx4 v[230:233], v238, s[98:99] offset:128
	global_load_dwordx4 v[166:169], v206, s[100:101] offset:128
	global_load_dwordx4 v[170:173], v207, s[100:101] offset:128
	global_load_dwordx4 v[174:177], v208, s[100:101] offset:128
	global_load_dwordx4 v[190:193], v238, s[100:101] offset:128
	s_add_u32 s98, s98, 0x100
	s_addc_u32 s99, s99, 0
	s_add_u32 s100, s100, 0x100
	s_addc_u32 s101, s101, 0
.Lg3_nonext_m0:
	v_lshrrev_b32_e32 v237, 8, v165
	v_and_b32_e32 v194, 31, v165
	v_lshl_or_b32 v237, v237, 7, v194
	v_mul_u32_u24_e32 v236, 0x208, v237
	v_bfe_u32 v237, v165, 6, 2
	v_bfe_u32 v194, v165, 5, 1
	v_lshlrev_b32_e32 v237, 7, v237
	v_lshl_or_b32 v237, v194, 3, v237
	v_add_u32_e32 v236, v236, v237
	v_cvt_pk_bf16_f32 v114, v114, v115
	v_cvt_pk_bf16_f32 v115, v116, v117
	v_cvt_pk_bf16_f32 v118, v118, v119
	v_cvt_pk_bf16_f32 v119, v120, v121
	v_cvt_pk_bf16_f32 v122, v122, v123
	v_cvt_pk_bf16_f32 v123, v124, v125
	v_cvt_pk_bf16_f32 v126, v126, v127
	v_cvt_pk_bf16_f32 v127, v128, v129
	s_barrier
	ds_write_b64 v236, v[114:115]
	ds_write_b64 v236, v[118:119] offset:16
	ds_write_b64 v236, v[122:123] offset:32
	ds_write_b64 v236, v[126:127] offset:48
	v_cvt_pk_bf16_f32 v98, v98, v99
	v_cvt_pk_bf16_f32 v99, v100, v101
	v_cvt_pk_bf16_f32 v102, v102, v103
	v_cvt_pk_bf16_f32 v103, v104, v105
	v_cvt_pk_bf16_f32 v106, v106, v107
	v_cvt_pk_bf16_f32 v107, v108, v109
	v_cvt_pk_bf16_f32 v110, v110, v111
	v_cvt_pk_bf16_f32 v111, v112, v113
	ds_write_b64 v236, v[98:99] offset:64
	ds_write_b64 v236, v[102:103] offset:80
	ds_write_b64 v236, v[106:107] offset:96
	ds_write_b64 v236, v[110:111] offset:112
	v_cvt_pk_bf16_f32 v82, v82, v83
	v_cvt_pk_bf16_f32 v83, v84, v85
	v_cvt_pk_bf16_f32 v86, v86, v87
	v_cvt_pk_bf16_f32 v87, v88, v89
	v_cvt_pk_bf16_f32 v90, v90, v91
	v_cvt_pk_bf16_f32 v91, v92, v93
	v_cvt_pk_bf16_f32 v94, v94, v95
	v_cvt_pk_bf16_f32 v95, v96, v97
	ds_write_b64 v236, v[82:83] offset:16640
	ds_write_b64 v236, v[86:87] offset:16656
	ds_write_b64 v236, v[90:91] offset:16672
	ds_write_b64 v236, v[94:95] offset:16688
	v_cvt_pk_bf16_f32 v66, v66, v67
	v_cvt_pk_bf16_f32 v67, v68, v69
	v_cvt_pk_bf16_f32 v70, v70, v71
	v_cvt_pk_bf16_f32 v71, v72, v73
	v_cvt_pk_bf16_f32 v74, v74, v75
	v_cvt_pk_bf16_f32 v75, v76, v77
	v_cvt_pk_bf16_f32 v78, v78, v79
	v_cvt_pk_bf16_f32 v79, v80, v81
	ds_write_b64 v236, v[66:67] offset:16704
	ds_write_b64 v236, v[70:71] offset:16720
	ds_write_b64 v236, v[74:75] offset:16736
	ds_write_b64 v236, v[78:79] offset:16752
	v_cvt_pk_bf16_f32 v50, v50, v51
	v_cvt_pk_bf16_f32 v51, v52, v53
	v_cvt_pk_bf16_f32 v54, v54, v55
	v_cvt_pk_bf16_f32 v55, v56, v57
	v_cvt_pk_bf16_f32 v58, v58, v59
	v_cvt_pk_bf16_f32 v59, v60, v61
	v_cvt_pk_bf16_f32 v62, v62, v63
	v_cvt_pk_bf16_f32 v63, v64, v65
	ds_write_b64 v236, v[50:51] offset:33280
	ds_write_b64 v236, v[54:55] offset:33296
	ds_write_b64 v236, v[58:59] offset:33312
	ds_write_b64 v236, v[62:63] offset:33328
	v_cvt_pk_bf16_f32 v34, v34, v35
	v_cvt_pk_bf16_f32 v35, v36, v37
	v_cvt_pk_bf16_f32 v38, v38, v39
	v_cvt_pk_bf16_f32 v39, v40, v41
	v_cvt_pk_bf16_f32 v42, v42, v43
	v_cvt_pk_bf16_f32 v43, v44, v45
	v_cvt_pk_bf16_f32 v46, v46, v47
	v_cvt_pk_bf16_f32 v47, v48, v49
	ds_write_b64 v236, v[34:35] offset:33344
	ds_write_b64 v236, v[38:39] offset:33360
	ds_write_b64 v236, v[42:43] offset:33376
	ds_write_b64 v236, v[46:47] offset:33392
	v_cvt_pk_bf16_f32 v18, v18, v19
	v_cvt_pk_bf16_f32 v19, v20, v21
	v_cvt_pk_bf16_f32 v22, v22, v23
	v_cvt_pk_bf16_f32 v23, v24, v25
	v_cvt_pk_bf16_f32 v26, v26, v27
	v_cvt_pk_bf16_f32 v27, v28, v29
	v_cvt_pk_bf16_f32 v30, v30, v31
	v_cvt_pk_bf16_f32 v31, v32, v33
	ds_write_b64 v236, v[18:19] offset:49920
	ds_write_b64 v236, v[22:23] offset:49936
	ds_write_b64 v236, v[26:27] offset:49952
	ds_write_b64 v236, v[30:31] offset:49968
	v_cvt_pk_bf16_f32 v2, v2, v3
	v_cvt_pk_bf16_f32 v3, v4, v5
	v_cvt_pk_bf16_f32 v6, v6, v7
	v_cvt_pk_bf16_f32 v7, v8, v9
	v_cvt_pk_bf16_f32 v10, v10, v11
	v_cvt_pk_bf16_f32 v11, v12, v13
	v_cvt_pk_bf16_f32 v14, v14, v15
	v_cvt_pk_bf16_f32 v15, v16, v17
	ds_write_b64 v236, v[2:3] offset:49984
	ds_write_b64 v236, v[6:7] offset:50000
	ds_write_b64 v236, v[10:11] offset:50016
	ds_write_b64 v236, v[14:15] offset:50032
	s_waitcnt lgkmcnt(0)
	s_barrier
; DI void gemm_phase(const Params& p, int layer, int mode, int nrows, char* lds_all) {
;     ...
;         for (int idx = tid; idx < 128 * 32; idx += 512) {
;           const int rr = idx >> 5, c8 = (idx & 31) * 8;
;           const int row = m0 + half * 128 + rr, col = n0 + c8;
;           const float4 v0 = *(const float4*)(Cs + rr * CSW + c8), v1 = *(const float4*)(Cs + rr * CSW + c8 + 4);
;           if (mode == 0) {
;             uint4 o;
;             o.x = pack2(v0.x, v0.y); o.y = pack2(v0.z, v0.w); o.z = pack2(v1.x, v1.y); o.w = pack2(v1.z, v1.w);
;             *(uint4*)((u16*)(p.ws + O_Z) + (size_t)row * ZW + col) = o;
	v_lshrrev_b32_e32 v237, 5, v165
	v_and_b32_e32 v194, 31, v165
	v_mul_u32_u24_e32 v235, 0x208, v237
	v_lshl_add_u32 v235, v194, 4, v235
	ds_read2_b64 v[2:5], v235 offset1:1
	v_add_u32_e32 v235, 0x2080, v235
	ds_read2_b64 v[6:9], v235 offset1:1
	v_add_u32_e32 v235, 0x2080, v235
	ds_read2_b64 v[10:13], v235 offset1:1
	v_add_u32_e32 v235, 0x2080, v235
	ds_read2_b64 v[14:17], v235 offset1:1
	v_add_u32_e32 v235, 0x2080, v235
	ds_read2_b64 v[18:21], v235 offset1:1
	v_add_u32_e32 v235, 0x2080, v235
	ds_read2_b64 v[22:25], v235 offset1:1
	v_add_u32_e32 v235, 0x2080, v235
	ds_read2_b64 v[26:29], v235 offset1:1
	v_add_u32_e32 v235, 0x2080, v235
	ds_read2_b64 v[30:33], v235 offset1:1
	v_add_u32_e32 v235, 0x2080, v235
	ds_read2_b64 v[34:37], v235 offset1:1
	v_add_u32_e32 v235, 0x2080, v235
	ds_read2_b64 v[38:41], v235 offset1:1
	v_add_u32_e32 v235, 0x2080, v235
	ds_read2_b64 v[42:45], v235 offset1:1
	v_add_u32_e32 v235, 0x2080, v235
	ds_read2_b64 v[46:49], v235 offset1:1
	v_add_u32_e32 v235, 0x2080, v235
	ds_read2_b64 v[50:53], v235 offset1:1
	v_add_u32_e32 v235, 0x2080, v235
	ds_read2_b64 v[54:57], v235 offset1:1
	v_add_u32_e32 v235, 0x2080, v235
	ds_read2_b64 v[58:61], v235 offset1:1
	v_add_u32_e32 v235, 0x2080, v235
	ds_read2_b64 v[62:65], v235 offset1:1
	s_waitcnt lgkmcnt(15)
	global_store_dwordx4 v234, v[2:5], s[50:51]
	v_add_u32_e32 v234, 0x16000, v234
	s_waitcnt lgkmcnt(14)
	global_store_dwordx4 v234, v[6:9], s[50:51]
	v_add_u32_e32 v234, 0x16000, v234
	s_waitcnt lgkmcnt(13)
	global_store_dwordx4 v234, v[10:13], s[50:51]
	v_add_u32_e32 v234, 0x16000, v234
	s_waitcnt lgkmcnt(12)
	global_store_dwordx4 v234, v[14:17], s[50:51]
	v_add_u32_e32 v234, 0x16000, v234
	s_waitcnt lgkmcnt(11)
	global_store_dwordx4 v234, v[18:21], s[50:51]
	v_add_u32_e32 v234, 0x16000, v234
	s_waitcnt lgkmcnt(10)
	global_store_dwordx4 v234, v[22:25], s[50:51]
	v_add_u32_e32 v234, 0x16000, v234
	s_waitcnt lgkmcnt(9)
	global_store_dwordx4 v234, v[26:29], s[50:51]
	v_add_u32_e32 v234, 0x16000, v234
	s_waitcnt lgkmcnt(8)
	global_store_dwordx4 v234, v[30:33], s[50:51]
	v_add_u32_e32 v234, 0x16000, v234
	s_waitcnt lgkmcnt(7)
	global_store_dwordx4 v234, v[34:37], s[50:51]
	v_add_u32_e32 v234, 0x16000, v234
	s_waitcnt lgkmcnt(6)
	global_store_dwordx4 v234, v[38:41], s[50:51]
	v_add_u32_e32 v234, 0x16000, v234
	s_waitcnt lgkmcnt(5)
	global_store_dwordx4 v234, v[42:45], s[50:51]
	v_add_u32_e32 v234, 0x16000, v234
	s_waitcnt lgkmcnt(4)
	global_store_dwordx4 v234, v[46:49], s[50:51]
	v_add_u32_e32 v234, 0x16000, v234
	s_waitcnt lgkmcnt(3)
	global_store_dwordx4 v234, v[50:53], s[50:51]
	v_add_u32_e32 v234, 0x16000, v234
	s_waitcnt lgkmcnt(2)
	global_store_dwordx4 v234, v[54:57], s[50:51]
	v_add_u32_e32 v234, 0x16000, v234
	s_waitcnt lgkmcnt(1)
	global_store_dwordx4 v234, v[58:61], s[50:51]
	v_add_u32_e32 v234, 0x16000, v234
	s_waitcnt lgkmcnt(0)
	global_store_dwordx4 v234, v[62:65], s[50:51]
	s_cmp_lg_u32 s10, 0
	s_cbranch_scc1 .Lg3_start_m0
	v_mov_b32_e32 v190, 0x10c20
	v_mov_b32_e32 v191, 0x11040
	v_mov_b32_e32 v192, 0x11460
	v_mov_b32_e32 v193, 0x12900
	v_mov_b32_e32 v194, 0x12d20
	v_mov_b32_e32 v195, 0x13140
	v_mov_b32_e32 v196, 0x13560
	v_mov_b32_e32 v197, 0x14a00
	v_mov_b32_e32 v198, 0x14e20
	v_mov_b32_e32 v199, 0x15240
	v_mov_b32_e32 v200, 0x15660
	v_mov_b32_e32 v201, 0x16b00
	v_mov_b32_e32 v202, 0x16f20
	v_mov_b32_e32 v203, 0x17340
	v_mov_b32_e32 v204, 0x17760
	v_mov_b32_e32 v205, 0x18c00
	v_mov_b32_e32 v206, 0x19020
	v_mov_b32_e32 v207, 0x19440
	v_mov_b32_e32 v208, 0x10800
	s_branch .LBB0_209

; #define G5_LOAD(k0)                                                                 \
;   {                                                                                 \
;     _Pragma("unroll") for (int i_ = 0; i_ < 4; ++i_) ra[i_] = ldg16(Ap + (size_t)(i_ * 64) * lda + (k0)); \
;     _Pragma("unroll") for (int i_ = 0; i_ < 4; ++i_) rb[i_] = ldg16(Bp + (size_t)(i_ * 64) * ldb + (k0)); \
;   }
; #define G5_STORE(s)                                                                 \
;   {                                                                                 \
;     _Pragma("unroll") for (int i_ = 0; i_ < 4; ++i_) *(u32x4*)(Sw + (s) * STG + i_ * 64 * GS) = ra[i_]; \
;     _Pragma("unroll") for (int i_ = 0; i_ < 4; ++i_) *(u32x4*)(Sw + (s) * STG + 256 * GS + i_ * 64 * GS) = rb[i_]; \
;   }
; template <typename Epi>
; DI void gemm_tile512(const u16* __restrict__ A, int lda, const u16* __restrict__ Bt, int ldb, int K, char* lds_all, Epi epi) {
;     ...
;   const int nk = K >> 6;
;   __syncthreads();
;   G5_LOAD(0);
;   G5_STORE(0);
;   G5_LOAD(64);
;   __syncthreads();
; DI void gemm_phase(const Params& p, int layer, int mode, int nrows, char* lds_all) {
;     ...
;   for (int i = jb;; i += nj) {
;     const int srl = i / per, rem = i - srl * per;
;     const int sr = xcd + nx * srl;
;     if (sr >= nsr) break;
;     const int tn = rem >> 1, tm = sr * 2 + (rem & 1);
;     const int m0 = tm * 256, n0 = tn * 256;
;     gemm_tile512(A + (size_t)m0 * lda, lda, Bt + (size_t)n0 * ldb, ldb, K, lds_all, [&](int half) {
.LBB0_833:
	s_lshl_b32 s11, s5, 9
	s_lshl_b32 s5, s21, 8
	s_and_b32 s5, s5, 0x100
	s_lshl_b32 s24, s4, 12
	s_lshl_b32 s4, s21, 7
	s_or_b32 s22, s5, s11
	s_sub_i32 s4, s4, s24
	s_and_b32 s23, s4, 0xffffff00
	s_mul_i32 s4, s22, 0x900
	v_readlane_b32 s8, v250, 46
	s_mul_hi_i32 s5, s22, 0x900
	s_add_u32 s4, s8, s4
	v_readlane_b32 s8, v250, 47
	s_addc_u32 s5, s8, s5
	s_mul_i32 s8, s23, 0x900
	s_mul_hi_i32 s9, s23, 0x900
	s_add_u32 s8, s14, s8
	s_addc_u32 s9, s15, s9
	s_mov_b64 s[26:27], s[4:5]
	s_mov_b64 s[98:99], s[26:27]
	s_mov_b64 s[100:101], s[8:9]
	v_lshrrev_b32_e32 v239, 3, v165
	v_and_b32_e32 v0, 7, v165
	v_mul_u32_u24_e32 v206, 0x900, v239
	v_lshl_add_u32 v206, v0, 4, v206
	v_add_u32_e32 v207, 0x24000, v206
	v_add_u32_e32 v208, 0x48000, v206
	v_add_u32_e32 v238, 0x6c000, v206
	global_load_dwordx4 v[130:133], v206, s[98:99]
	global_load_dwordx4 v[134:137], v207, s[98:99]
	global_load_dwordx4 v[138:141], v208, s[98:99]
	global_load_dwordx4 v[142:145], v238, s[98:99]
	global_load_dwordx4 v[146:149], v206, s[100:101]
	global_load_dwordx4 v[150:153], v207, s[100:101]
	global_load_dwordx4 v[154:157], v208, s[100:101]
	global_load_dwordx4 v[158:161], v238, s[100:101]
	global_load_dwordx4 v[218:221], v206, s[98:99] offset:128
	global_load_dwordx4 v[222:225], v207, s[98:99] offset:128
	global_load_dwordx4 v[226:229], v208, s[98:99] offset:128
	global_load_dwordx4 v[230:233], v238, s[98:99] offset:128
	global_load_dwordx4 v[166:169], v206, s[100:101] offset:128
	global_load_dwordx4 v[170:173], v207, s[100:101] offset:128
	global_load_dwordx4 v[174:177], v208, s[100:101] offset:128
	global_load_dwordx4 v[190:193], v238, s[100:101] offset:128
	s_add_u32 s98, s98, 0x100
	s_addc_u32 s99, s99, 0
	s_add_u32 s100, s100, 0x100
	s_addc_u32 s101, s101, 0
	v_lshrrev_b32_e32 v239, 3, v165
	v_and_b32_e32 v0, 7, v165
	v_mul_u32_u24_e32 v180, 0x90, v239
	v_lshl_add_u32 v180, v0, 4, v180
	v_and_b32_e32 v239, 31, v165
	v_bfe_u32 v0, v165, 5, 1
	v_lshrrev_b32_e32 v179, 8, v165
	v_lshl_or_b32 v178, v179, 7, v239
	v_mul_u32_u24_e32 v178, 0x90, v178
	v_lshl_add_u32 v178, v0, 4, v178
	v_bfe_u32 v179, v165, 6, 2
	v_lshl_or_b32 v179, v179, 6, v239
	v_mul_u32_u24_e32 v179, 0x90, v179
	v_lshl_add_u32 v179, v0, 4, v179
	s_mov_b32 s11, 0x12000
	s_mov_b32 s12, 13
	s_barrier
	s_waitcnt vmcnt(15)
	ds_write_b128 v180, v[130:133]
	s_waitcnt vmcnt(14)
	ds_write_b128 v180, v[134:137] offset:9216
	s_waitcnt vmcnt(13)
	ds_write_b128 v180, v[138:141] offset:18432
	s_waitcnt vmcnt(12)
	ds_write_b128 v180, v[142:145] offset:27648
	s_waitcnt vmcnt(11)
	ds_write_b128 v180, v[146:149] offset:36864
	s_waitcnt vmcnt(10)
	ds_write_b128 v180, v[150:153] offset:46080
	s_waitcnt vmcnt(9)
	ds_write_b128 v180, v[154:157] offset:55296
	s_waitcnt vmcnt(8)
	ds_write_b128 v180, v[158:161] offset:64512
	v_add_u32_e32 v180, 0x12000, v180
	s_waitcnt vmcnt(7)
	ds_write_b128 v180, v[218:221]
	s_waitcnt vmcnt(6)
	ds_write_b128 v180, v[222:225] offset:9216
	s_waitcnt vmcnt(5)
	ds_write_b128 v180, v[226:229] offset:18432
	s_waitcnt vmcnt(4)
	ds_write_b128 v180, v[230:233] offset:27648
	s_waitcnt vmcnt(3)
	ds_write_b128 v180, v[166:169] offset:36864
	s_waitcnt vmcnt(2)
	ds_write_b128 v180, v[170:173] offset:46080
	s_waitcnt vmcnt(1)
	ds_write_b128 v180, v[174:177] offset:55296
	s_waitcnt vmcnt(0)
	ds_write_b128 v180, v[190:193] offset:64512
	s_waitcnt lgkmcnt(0)
	s_branch .Lg3_k_m2
.Lg3_start_m2:
	v_lshrrev_b32_e32 v239, 3, v165
	v_and_b32_e32 v0, 7, v165
	v_mul_u32_u24_e32 v180, 0x90, v239
	v_lshl_add_u32 v180, v0, 4, v180
	v_and_b32_e32 v239, 31, v165
	v_bfe_u32 v0, v165, 5, 1
	v_lshrrev_b32_e32 v179, 8, v165
	v_lshl_or_b32 v178, v179, 7, v239
	v_mul_u32_u24_e32 v178, 0x90, v178
	v_lshl_add_u32 v178, v0, 4, v178
	v_bfe_u32 v179, v165, 6, 2
	v_lshl_or_b32 v179, v179, 6, v239
	v_mul_u32_u24_e32 v179, 0x90, v179
	v_lshl_add_u32 v179, v0, 4, v179
	s_mov_b32 s11, 0x12000
	s_mov_b32 s12, 13
	s_barrier
	s_waitcnt vmcnt(31)
	ds_write_b128 v180, v[130:133]
	s_waitcnt vmcnt(30)
	ds_write_b128 v180, v[134:137] offset:9216
	s_waitcnt vmcnt(29)
	ds_write_b128 v180, v[138:141] offset:18432
	s_waitcnt vmcnt(28)
	ds_write_b128 v180, v[142:145] offset:27648
	s_waitcnt vmcnt(27)
	ds_write_b128 v180, v[146:149] offset:36864
	s_waitcnt vmcnt(26)
	ds_write_b128 v180, v[150:153] offset:46080
	s_waitcnt vmcnt(25)
	ds_write_b128 v180, v[154:157] offset:55296
	s_waitcnt vmcnt(24)
	ds_write_b128 v180, v[158:161] offset:64512
	v_add_u32_e32 v180, 0x12000, v180
	s_waitcnt vmcnt(23)
	ds_write_b128 v180, v[218:221]
	s_waitcnt vmcnt(22)
	ds_write_b128 v180, v[222:225] offset:9216
	s_waitcnt vmcnt(21)
	ds_write_b128 v180, v[226:229] offset:18432
	s_waitcnt vmcnt(20)
	ds_write_b128 v180, v[230:233] offset:27648
	s_waitcnt vmcnt(19)
	ds_write_b128 v180, v[166:169] offset:36864
	s_waitcnt vmcnt(18)
	ds_write_b128 v180, v[170:173] offset:46080
	s_waitcnt vmcnt(17)
	ds_write_b128 v180, v[174:177] offset:55296
	s_waitcnt vmcnt(16)
	ds_write_b128 v180, v[190:193] offset:64512
	s_waitcnt lgkmcnt(0)
; #define G5_LOAD(k0)                                                                 \
;   {                                                                                 \
;     _Pragma("unroll") for (int i_ = 0; i_ < 4; ++i_) ra[i_] = ldg16(Ap + (size_t)(i_ * 64) * lda + (k0)); \
;     _Pragma("unroll") for (int i_ = 0; i_ < 4; ++i_) rb[i_] = ldg16(Bp + (size_t)(i_ * 64) * ldb + (k0)); \
;   }
; #define G5_STORE(s)                                                                 \
;   {                                                                                 \
;     _Pragma("unroll") for (int i_ = 0; i_ < 4; ++i_) *(u32x4*)(Sw + (s) * STG + i_ * 64 * GS) = ra[i_]; \
;     _Pragma("unroll") for (int i_ = 0; i_ < 4; ++i_) *(u32x4*)(Sw + (s) * STG + 256 * GS + i_ * 64 * GS) = rb[i_]; \
;   }
; template <typename Epi>
; DI void gemm_tile512(const u16* __restrict__ A, int lda, const u16* __restrict__ Bt, int ldb, int K, char* lds_all, Epi epi) {
;     ...
;   for (int kt = 0; kt + 2 < nk; ++kt) {
;     const int cur = kt & 1;
;     G5_COMPUTE(cur);
;     G5_STORE(cur ^ 1);
;     G5_LOAD((kt + 2) << 6);
;     __syncthreads();
;   }
.Lg3_k_m2:
	s_barrier
	ds_read_b128 v[194:197], v179 offset:36864
	ds_read_b128 v[166:169], v178
	ds_read_b128 v[198:201], v179 offset:41472
	ds_read_b128 v[170:173], v178 offset:4608
	ds_read_b128 v[174:177], v178 offset:9216
	ds_read_b128 v[190:193], v178 offset:13824
	s_waitcnt lgkmcnt(4)
	v_mfma_f32_32x32x16_bf16 v[114:129], v[194:197], v[166:169], 0
	ds_read_b128 v[234:237], v179 offset:36896
	s_waitcnt lgkmcnt(4)
	v_mfma_f32_32x32x16_bf16 v[98:113], v[198:201], v[166:169], 0
	ds_read_b128 v[218:221], v178 offset:32
	global_load_dwordx4 v[130:133], v206, s[98:99]
	s_waitcnt lgkmcnt(4)
	v_mfma_f32_32x32x16_bf16 v[82:97], v[194:197], v[170:173], 0
	ds_read_b128 v[202:205], v179 offset:41504
	v_mfma_f32_32x32x16_bf16 v[66:81], v[198:201], v[170:173], 0
	ds_read_b128 v[222:225], v178 offset:4640
	global_load_dwordx4 v[134:137], v207, s[98:99]
	s_waitcnt lgkmcnt(5)
	v_mfma_f32_32x32x16_bf16 v[50:65], v[194:197], v[174:177], 0
	ds_read_b128 v[226:229], v178 offset:9248
	v_mfma_f32_32x32x16_bf16 v[34:49], v[198:201], v[174:177], 0
	ds_read_b128 v[230:233], v178 offset:13856
	global_load_dwordx4 v[138:141], v208, s[98:99]
	s_waitcnt lgkmcnt(6)
	v_mfma_f32_32x32x16_bf16 v[18:33], v[194:197], v[190:193], 0
	v_mfma_f32_32x32x16_bf16 v[2:17], v[198:201], v[190:193], 0
	global_load_dwordx4 v[142:145], v238, s[98:99]
	s_waitcnt lgkmcnt(4)
	v_mfma_f32_32x32x16_bf16 v[114:129], v[234:237], v[218:221], v[114:129]
	ds_read_b128 v[194:197], v179 offset:36928
	s_waitcnt lgkmcnt(4)
	v_mfma_f32_32x32x16_bf16 v[98:113], v[202:205], v[218:221], v[98:113]
	ds_read_b128 v[166:169], v178 offset:64
	global_load_dwordx4 v[146:149], v206, s[100:101]
	s_waitcnt lgkmcnt(4)
	v_mfma_f32_32x32x16_bf16 v[82:97], v[234:237], v[222:225], v[82:97]
	ds_read_b128 v[198:201], v179 offset:41536
	v_mfma_f32_32x32x16_bf16 v[66:81], v[202:205], v[222:225], v[66:81]
	ds_read_b128 v[170:173], v178 offset:4672
	global_load_dwordx4 v[150:153], v207, s[100:101]
	s_waitcnt lgkmcnt(5)
	v_mfma_f32_32x32x16_bf16 v[50:65], v[234:237], v[226:229], v[50:65]
	ds_read_b128 v[174:177], v178 offset:9280
	v_mfma_f32_32x32x16_bf16 v[34:49], v[202:205], v[226:229], v[34:49]
	ds_read_b128 v[190:193], v178 offset:13888
	global_load_dwordx4 v[154:157], v208, s[100:101]
	s_waitcnt lgkmcnt(6)
	v_mfma_f32_32x32x16_bf16 v[18:33], v[234:237], v[230:233], v[18:33]
	v_mfma_f32_32x32x16_bf16 v[2:17], v[202:205], v[230:233], v[2:17]
	global_load_dwordx4 v[158:161], v238, s[100:101]
	v_subrev_u32_e32 v180, s11, v180
	s_waitcnt lgkmcnt(4)
	v_mfma_f32_32x32x16_bf16 v[114:129], v[194:197], v[166:169], v[114:129]
	ds_read_b128 v[234:237], v179 offset:36960
	s_waitcnt lgkmcnt(4)
	v_mfma_f32_32x32x16_bf16 v[98:113], v[198:201], v[166:169], v[98:113]
	ds_read_b128 v[218:221], v178 offset:96
	s_waitcnt lgkmcnt(4)
	v_mfma_f32_32x32x16_bf16 v[82:97], v[194:197], v[170:173], v[82:97]
	ds_read_b128 v[202:205], v179 offset:41568
	v_mfma_f32_32x32x16_bf16 v[66:81], v[198:201], v[170:173], v[66:81]
	ds_read_b128 v[222:225], v178 offset:4704
	s_waitcnt lgkmcnt(5)
	v_mfma_f32_32x32x16_bf16 v[50:65], v[194:197], v[174:177], v[50:65]
	ds_read_b128 v[226:229], v178 offset:9312
	v_mfma_f32_32x32x16_bf16 v[34:49], v[198:201], v[174:177], v[34:49]
	ds_read_b128 v[230:233], v178 offset:13920
	v_add_u32_e32 v178, s11, v178
	v_add_u32_e32 v179, s11, v179
	s_waitcnt lgkmcnt(6)
	v_mfma_f32_32x32x16_bf16 v[18:33], v[194:197], v[190:193], v[18:33]
	v_mfma_f32_32x32x16_bf16 v[2:17], v[198:201], v[190:193], v[2:17]
	s_sub_u32 s11, 0, s11
	s_add_u32 s98, s98, 0x80
	s_addc_u32 s99, s99, 0
	s_add_u32 s100, s100, 0x80
	s_addc_u32 s101, s101, 0
	s_waitcnt lgkmcnt(0)
.Lg3_loop_m2:
	s_barrier
	ds_read_b128 v[194:197], v179 offset:36864
	ds_read_b128 v[166:169], v178
	v_mfma_f32_32x32x16_bf16 v[114:129], v[234:237], v[218:221], v[114:129]
	ds_read_b128 v[198:201], v179 offset:41472
	v_mfma_f32_32x32x16_bf16 v[98:113], v[202:205], v[218:221], v[98:113]
	ds_read_b128 v[170:173], v178 offset:4608
	v_mfma_f32_32x32x16_bf16 v[82:97], v[234:237], v[222:225], v[82:97]
	ds_read_b128 v[174:177], v178 offset:9216
	v_mfma_f32_32x32x16_bf16 v[66:81], v[202:205], v[222:225], v[66:81]
	ds_read_b128 v[190:193], v178 offset:13824
	v_mfma_f32_32x32x16_bf16 v[50:65], v[234:237], v[226:229], v[50:65]
	v_mfma_f32_32x32x16_bf16 v[34:49], v[202:205], v[226:229], v[34:49]
	v_mfma_f32_32x32x16_bf16 v[18:33], v[234:237], v[230:233], v[18:33]
	v_mfma_f32_32x32x16_bf16 v[2:17], v[202:205], v[230:233], v[2:17]
	s_waitcnt lgkmcnt(4)
	v_mfma_f32_32x32x16_bf16 v[114:129], v[194:197], v[166:169], v[114:129]
	ds_read_b128 v[234:237], v179 offset:36896
	s_waitcnt lgkmcnt(4)
	v_mfma_f32_32x32x16_bf16 v[98:113], v[198:201], v[166:169], v[98:113]
	ds_read_b128 v[218:221], v178 offset:32
	s_waitcnt vmcnt(7)
	ds_write_b128 v180, v[130:133]
	global_load_dwordx4 v[130:133], v206, s[98:99]
	s_waitcnt lgkmcnt(5)
	v_mfma_f32_32x32x16_bf16 v[82:97], v[194:197], v[170:173], v[82:97]
	ds_read_b128 v[202:205], v179 offset:41504
	v_mfma_f32_32x32x16_bf16 v[66:81], v[198:201], v[170:173], v[66:81]
	ds_read_b128 v[222:225], v178 offset:4640
	s_waitcnt vmcnt(7)
	ds_write_b128 v180, v[134:137] offset:9216
	global_load_dwordx4 v[134:137], v207, s[98:99]
	s_waitcnt lgkmcnt(7)
	v_mfma_f32_32x32x16_bf16 v[50:65], v[194:197], v[174:177], v[50:65]
	ds_read_b128 v[226:229], v178 offset:9248
	v_mfma_f32_32x32x16_bf16 v[34:49], v[198:201], v[174:177], v[34:49]
	ds_read_b128 v[230:233], v178 offset:13856
	s_waitcnt vmcnt(7)
	ds_write_b128 v180, v[138:141] offset:18432
	global_load_dwordx4 v[138:141], v208, s[98:99]
	s_waitcnt lgkmcnt(9)
; #define G5_LOAD(k0)                                                                 \
;   {                                                                                 \
;     _Pragma("unroll") for (int i_ = 0; i_ < 4; ++i_) ra[i_] = ldg16(Ap + (size_t)(i_ * 64) * lda + (k0)); \
;     _Pragma("unroll") for (int i_ = 0; i_ < 4; ++i_) rb[i_] = ldg16(Bp + (size_t)(i_ * 64) * ldb + (k0)); \
;   }
; #define G5_STORE(s)                                                                 \
;   {                                                                                 \
;     _Pragma("unroll") for (int i_ = 0; i_ < 4; ++i_) *(u32x4*)(Sw + (s) * STG + i_ * 64 * GS) = ra[i_]; \
;     _Pragma("unroll") for (int i_ = 0; i_ < 4; ++i_) *(u32x4*)(Sw + (s) * STG + 256 * GS + i_ * 64 * GS) = rb[i_]; \
;   }
; template <typename Epi>
; DI void gemm_tile512(const u16* __restrict__ A, int lda, const u16* __restrict__ Bt, int ldb, int K, char* lds_all, Epi epi) {
;     ...
;   const int nk = K >> 6;
;   __syncthreads();
;   G5_LOAD(0);
;   G5_STORE(0);
;   G5_LOAD(64);
;   __syncthreads();
;   for (int kt = 0; kt + 2 < nk; ++kt) {
;     const int cur = kt & 1;
;     G5_COMPUTE(cur);
;     G5_STORE(cur ^ 1);
;     G5_LOAD((kt + 2) << 6);
;     __syncthreads();
;   }
;   {
;     const int cur = (nk - 2) & 1;
;     G5_COMPUTE(cur);
;     G5_STORE(cur ^ 1);
	v_mfma_f32_32x32x16_bf16 v[18:33], v[194:197], v[190:193], v[18:33]
	v_mfma_f32_32x32x16_bf16 v[2:17], v[198:201], v[190:193], v[2:17]
	s_waitcnt vmcnt(7)
	ds_write_b128 v180, v[142:145] offset:27648
	global_load_dwordx4 v[142:145], v238, s[98:99]
	s_waitcnt lgkmcnt(8)
	v_mfma_f32_32x32x16_bf16 v[114:129], v[234:237], v[218:221], v[114:129]
	ds_read_b128 v[194:197], v179 offset:36928
	s_waitcnt lgkmcnt(7)
	v_mfma_f32_32x32x16_bf16 v[98:113], v[202:205], v[218:221], v[98:113]
	ds_read_b128 v[166:169], v178 offset:64
	s_waitcnt vmcnt(7)
	ds_write_b128 v180, v[146:149] offset:36864
	global_load_dwordx4 v[146:149], v206, s[100:101]
	s_waitcnt lgkmcnt(8)
	v_mfma_f32_32x32x16_bf16 v[82:97], v[234:237], v[222:225], v[82:97]
	ds_read_b128 v[198:201], v179 offset:41536
	v_mfma_f32_32x32x16_bf16 v[66:81], v[202:205], v[222:225], v[66:81]
	ds_read_b128 v[170:173], v178 offset:4672
	s_waitcnt vmcnt(7)
	ds_write_b128 v180, v[150:153] offset:46080
	global_load_dwordx4 v[150:153], v207, s[100:101]
	s_waitcnt lgkmcnt(9)
	v_mfma_f32_32x32x16_bf16 v[50:65], v[234:237], v[226:229], v[50:65]
	ds_read_b128 v[174:177], v178 offset:9280
	v_mfma_f32_32x32x16_bf16 v[34:49], v[202:205], v[226:229], v[34:49]
	ds_read_b128 v[190:193], v178 offset:13888
	s_waitcnt vmcnt(7)
	ds_write_b128 v180, v[154:157] offset:55296
	global_load_dwordx4 v[154:157], v208, s[100:101]
	s_waitcnt lgkmcnt(11)
	v_mfma_f32_32x32x16_bf16 v[18:33], v[234:237], v[230:233], v[18:33]
	v_mfma_f32_32x32x16_bf16 v[2:17], v[202:205], v[230:233], v[2:17]
	s_waitcnt vmcnt(7)
	ds_write_b128 v180, v[158:161] offset:64512
	global_load_dwordx4 v[158:161], v238, s[100:101]
	v_subrev_u32_e32 v180, s11, v180
	s_waitcnt lgkmcnt(8)
	v_mfma_f32_32x32x16_bf16 v[114:129], v[194:197], v[166:169], v[114:129]
	ds_read_b128 v[234:237], v179 offset:36960
	s_waitcnt lgkmcnt(7)
	v_mfma_f32_32x32x16_bf16 v[98:113], v[198:201], v[166:169], v[98:113]
	ds_read_b128 v[218:221], v178 offset:96
	s_waitcnt lgkmcnt(7)
	v_mfma_f32_32x32x16_bf16 v[82:97], v[194:197], v[170:173], v[82:97]
	ds_read_b128 v[202:205], v179 offset:41568
	v_mfma_f32_32x32x16_bf16 v[66:81], v[198:201], v[170:173], v[66:81]
	ds_read_b128 v[222:225], v178 offset:4704
	s_waitcnt lgkmcnt(7)
	v_mfma_f32_32x32x16_bf16 v[50:65], v[194:197], v[174:177], v[50:65]
	ds_read_b128 v[226:229], v178 offset:9312
	v_mfma_f32_32x32x16_bf16 v[34:49], v[198:201], v[174:177], v[34:49]
	ds_read_b128 v[230:233], v178 offset:13920
	v_add_u32_e32 v178, s11, v178
	v_add_u32_e32 v179, s11, v179
	s_waitcnt lgkmcnt(8)
	v_mfma_f32_32x32x16_bf16 v[18:33], v[194:197], v[190:193], v[18:33]
	v_mfma_f32_32x32x16_bf16 v[2:17], v[198:201], v[190:193], v[2:17]
	s_sub_u32 s11, 0, s11
	s_add_u32 s98, s98, 0x80
	s_addc_u32 s99, s99, 0
	s_add_u32 s100, s100, 0x80
	s_addc_u32 s101, s101, 0
	s_waitcnt lgkmcnt(0)
	s_sub_u32 s12, s12, 1
	s_cmp_lg_u32 s12, 0
	s_cbranch_scc1 .Lg3_loop_m2
	s_barrier
	ds_read_b128 v[194:197], v179 offset:36864
	ds_read_b128 v[166:169], v178
	v_mfma_f32_32x32x16_bf16 v[114:129], v[234:237], v[218:221], v[114:129]
	ds_read_b128 v[198:201], v179 offset:41472
	v_mfma_f32_32x32x16_bf16 v[98:113], v[202:205], v[218:221], v[98:113]
	ds_read_b128 v[170:173], v178 offset:4608
	v_mfma_f32_32x32x16_bf16 v[82:97], v[234:237], v[222:225], v[82:97]
	ds_read_b128 v[174:177], v178 offset:9216
	v_mfma_f32_32x32x16_bf16 v[66:81], v[202:205], v[222:225], v[66:81]
	ds_read_b128 v[190:193], v178 offset:13824
	v_mfma_f32_32x32x16_bf16 v[50:65], v[234:237], v[226:229], v[50:65]
	v_mfma_f32_32x32x16_bf16 v[34:49], v[202:205], v[226:229], v[34:49]
	v_mfma_f32_32x32x16_bf16 v[18:33], v[234:237], v[230:233], v[18:33]
	v_mfma_f32_32x32x16_bf16 v[2:17], v[202:205], v[230:233], v[2:17]
	s_waitcnt lgkmcnt(4)
	v_mfma_f32_32x32x16_bf16 v[114:129], v[194:197], v[166:169], v[114:129]
	ds_read_b128 v[234:237], v179 offset:36896
	s_waitcnt lgkmcnt(4)
	v_mfma_f32_32x32x16_bf16 v[98:113], v[198:201], v[166:169], v[98:113]
	ds_read_b128 v[218:221], v178 offset:32
	s_waitcnt vmcnt(7)
	ds_write_b128 v180, v[130:133]
	s_waitcnt lgkmcnt(5)
	v_mfma_f32_32x32x16_bf16 v[82:97], v[194:197], v[170:173], v[82:97]
	ds_read_b128 v[202:205], v179 offset:41504
	v_mfma_f32_32x32x16_bf16 v[66:81], v[198:201], v[170:173], v[66:81]
	ds_read_b128 v[222:225], v178 offset:4640
	s_waitcnt vmcnt(6)
	ds_write_b128 v180, v[134:137] offset:9216
	s_waitcnt lgkmcnt(7)
	v_mfma_f32_32x32x16_bf16 v[50:65], v[194:197], v[174:177], v[50:65]
	ds_read_b128 v[226:229], v178 offset:9248
	v_mfma_f32_32x32x16_bf16 v[34:49], v[198:201], v[174:177], v[34:49]
	ds_read_b128 v[230:233], v178 offset:13856
	s_waitcnt vmcnt(5)
	ds_write_b128 v180, v[138:141] offset:18432
	s_waitcnt lgkmcnt(9)
	v_mfma_f32_32x32x16_bf16 v[18:33], v[194:197], v[190:193], v[18:33]
	v_mfma_f32_32x32x16_bf16 v[2:17], v[198:201], v[190:193], v[2:17]
	s_waitcnt vmcnt(4)
	ds_write_b128 v180, v[142:145] offset:27648
	s_waitcnt lgkmcnt(8)
	v_mfma_f32_32x32x16_bf16 v[114:129], v[234:237], v[218:221], v[114:129]
	ds_read_b128 v[194:197], v179 offset:36928
	s_waitcnt lgkmcnt(7)
	v_mfma_f32_32x32x16_bf16 v[98:113], v[202:205], v[218:221], v[98:113]
	ds_read_b128 v[166:169], v178 offset:64
	s_waitcnt vmcnt(3)
	ds_write_b128 v180, v[146:149] offset:36864
	s_waitcnt lgkmcnt(8)
	v_mfma_f32_32x32x16_bf16 v[82:97], v[234:237], v[222:225], v[82:97]
	ds_read_b128 v[198:201], v179 offset:41536
	v_mfma_f32_32x32x16_bf16 v[66:81], v[202:205], v[222:225], v[66:81]
	ds_read_b128 v[170:173], v178 offset:4672
	s_waitcnt vmcnt(2)
	ds_write_b128 v180, v[150:153] offset:46080
	s_waitcnt lgkmcnt(9)
; #define G5_STORE(s)                                                                 \
;   {                                                                                 \
;     _Pragma("unroll") for (int i_ = 0; i_ < 4; ++i_) *(u32x4*)(Sw + (s) * STG + i_ * 64 * GS) = ra[i_]; \
;     _Pragma("unroll") for (int i_ = 0; i_ < 4; ++i_) *(u32x4*)(Sw + (s) * STG + 256 * GS + i_ * 64 * GS) = rb[i_]; \
;   }
; template <typename Epi>
; DI void gemm_tile512(const u16* __restrict__ A, int lda, const u16* __restrict__ Bt, int ldb, int K, char* lds_all, Epi epi) {
;     ...
;   {
;     const int cur = (nk - 2) & 1;
;     G5_COMPUTE(cur);
;     G5_STORE(cur ^ 1);
;     __syncthreads();
;     G5_COMPUTE(cur ^ 1);
;   }
; DI void gemm_phase(const Params& p, int layer, int mode, int nrows, char* lds_all) {
;     ...
;   for (int i = jb;; i += nj) {
;     const int srl = i / per, rem = i - srl * per;
;     const int sr = xcd + nx * srl;
;     if (sr >= nsr) break;
	v_mfma_f32_32x32x16_bf16 v[50:65], v[234:237], v[226:229], v[50:65]
	ds_read_b128 v[174:177], v178 offset:9280
	v_mfma_f32_32x32x16_bf16 v[34:49], v[202:205], v[226:229], v[34:49]
	ds_read_b128 v[190:193], v178 offset:13888
	s_waitcnt vmcnt(1)
	ds_write_b128 v180, v[154:157] offset:55296
	s_waitcnt lgkmcnt(11)
	v_mfma_f32_32x32x16_bf16 v[18:33], v[234:237], v[230:233], v[18:33]
	v_mfma_f32_32x32x16_bf16 v[2:17], v[202:205], v[230:233], v[2:17]
	s_waitcnt vmcnt(0)
	ds_write_b128 v180, v[158:161] offset:64512
	v_subrev_u32_e32 v180, s11, v180
	s_waitcnt lgkmcnt(8)
	v_mfma_f32_32x32x16_bf16 v[114:129], v[194:197], v[166:169], v[114:129]
	ds_read_b128 v[234:237], v179 offset:36960
	s_waitcnt lgkmcnt(7)
	v_mfma_f32_32x32x16_bf16 v[98:113], v[198:201], v[166:169], v[98:113]
	ds_read_b128 v[218:221], v178 offset:96
	s_waitcnt lgkmcnt(7)
	v_mfma_f32_32x32x16_bf16 v[82:97], v[194:197], v[170:173], v[82:97]
	ds_read_b128 v[202:205], v179 offset:41568
	v_mfma_f32_32x32x16_bf16 v[66:81], v[198:201], v[170:173], v[66:81]
	ds_read_b128 v[222:225], v178 offset:4704
	s_waitcnt lgkmcnt(7)
	v_mfma_f32_32x32x16_bf16 v[50:65], v[194:197], v[174:177], v[50:65]
	ds_read_b128 v[226:229], v178 offset:9312
	v_mfma_f32_32x32x16_bf16 v[34:49], v[198:201], v[174:177], v[34:49]
	ds_read_b128 v[230:233], v178 offset:13920
	v_add_u32_e32 v178, s11, v178
	v_add_u32_e32 v179, s11, v179
	s_waitcnt lgkmcnt(8)
	v_mfma_f32_32x32x16_bf16 v[18:33], v[194:197], v[190:193], v[18:33]
	v_mfma_f32_32x32x16_bf16 v[2:17], v[198:201], v[190:193], v[2:17]
	s_sub_u32 s11, 0, s11
	s_add_u32 s98, s98, 0x80
	s_addc_u32 s99, s99, 0
	s_add_u32 s100, s100, 0x80
	s_addc_u32 s101, s101, 0
	s_waitcnt lgkmcnt(0)
	s_barrier
	ds_read_b128 v[194:197], v179 offset:36864
	ds_read_b128 v[166:169], v178
	v_mfma_f32_32x32x16_bf16 v[114:129], v[234:237], v[218:221], v[114:129]
	ds_read_b128 v[198:201], v179 offset:41472
	v_mfma_f32_32x32x16_bf16 v[98:113], v[202:205], v[218:221], v[98:113]
	ds_read_b128 v[170:173], v178 offset:4608
	v_mfma_f32_32x32x16_bf16 v[82:97], v[234:237], v[222:225], v[82:97]
	ds_read_b128 v[174:177], v178 offset:9216
	v_mfma_f32_32x32x16_bf16 v[66:81], v[202:205], v[222:225], v[66:81]
	ds_read_b128 v[190:193], v178 offset:13824
	v_mfma_f32_32x32x16_bf16 v[50:65], v[234:237], v[226:229], v[50:65]
	v_mfma_f32_32x32x16_bf16 v[34:49], v[202:205], v[226:229], v[34:49]
	v_mfma_f32_32x32x16_bf16 v[18:33], v[234:237], v[230:233], v[18:33]
	v_mfma_f32_32x32x16_bf16 v[2:17], v[202:205], v[230:233], v[2:17]
	s_waitcnt lgkmcnt(4)
	v_mfma_f32_32x32x16_bf16 v[114:129], v[194:197], v[166:169], v[114:129]
	ds_read_b128 v[234:237], v179 offset:36896
	s_waitcnt lgkmcnt(4)
	v_mfma_f32_32x32x16_bf16 v[98:113], v[198:201], v[166:169], v[98:113]
	ds_read_b128 v[218:221], v178 offset:32
	s_waitcnt lgkmcnt(4)
	v_mfma_f32_32x32x16_bf16 v[82:97], v[194:197], v[170:173], v[82:97]
	ds_read_b128 v[202:205], v179 offset:41504
	v_mfma_f32_32x32x16_bf16 v[66:81], v[198:201], v[170:173], v[66:81]
	ds_read_b128 v[222:225], v178 offset:4640
	s_waitcnt lgkmcnt(5)
	v_mfma_f32_32x32x16_bf16 v[50:65], v[194:197], v[174:177], v[50:65]
	ds_read_b128 v[226:229], v178 offset:9248
	v_mfma_f32_32x32x16_bf16 v[34:49], v[198:201], v[174:177], v[34:49]
	ds_read_b128 v[230:233], v178 offset:13856
	s_waitcnt lgkmcnt(6)
	v_mfma_f32_32x32x16_bf16 v[18:33], v[194:197], v[190:193], v[18:33]
	v_mfma_f32_32x32x16_bf16 v[2:17], v[198:201], v[190:193], v[2:17]
	s_waitcnt lgkmcnt(4)
	v_mfma_f32_32x32x16_bf16 v[114:129], v[234:237], v[218:221], v[114:129]
	ds_read_b128 v[194:197], v179 offset:36928
	s_waitcnt lgkmcnt(4)
	v_mfma_f32_32x32x16_bf16 v[98:113], v[202:205], v[218:221], v[98:113]
	ds_read_b128 v[166:169], v178 offset:64
	s_waitcnt lgkmcnt(4)
	v_mfma_f32_32x32x16_bf16 v[82:97], v[234:237], v[222:225], v[82:97]
	ds_read_b128 v[198:201], v179 offset:41536
	v_mfma_f32_32x32x16_bf16 v[66:81], v[202:205], v[222:225], v[66:81]
	ds_read_b128 v[170:173], v178 offset:4672
	s_waitcnt lgkmcnt(5)
	v_mfma_f32_32x32x16_bf16 v[50:65], v[234:237], v[226:229], v[50:65]
	ds_read_b128 v[174:177], v178 offset:9280
	v_mfma_f32_32x32x16_bf16 v[34:49], v[202:205], v[226:229], v[34:49]
	ds_read_b128 v[190:193], v178 offset:13888
	s_waitcnt lgkmcnt(6)
	v_mfma_f32_32x32x16_bf16 v[18:33], v[234:237], v[230:233], v[18:33]
	v_mfma_f32_32x32x16_bf16 v[2:17], v[202:205], v[230:233], v[2:17]
	s_waitcnt lgkmcnt(4)
	v_mfma_f32_32x32x16_bf16 v[114:129], v[194:197], v[166:169], v[114:129]
	ds_read_b128 v[234:237], v179 offset:36960
	s_waitcnt lgkmcnt(4)
	v_mfma_f32_32x32x16_bf16 v[98:113], v[198:201], v[166:169], v[98:113]
	ds_read_b128 v[218:221], v178 offset:96
	s_waitcnt lgkmcnt(4)
	v_mfma_f32_32x32x16_bf16 v[82:97], v[194:197], v[170:173], v[82:97]
	ds_read_b128 v[202:205], v179 offset:41568
	v_mfma_f32_32x32x16_bf16 v[66:81], v[198:201], v[170:173], v[66:81]
	ds_read_b128 v[222:225], v178 offset:4704
	s_waitcnt lgkmcnt(5)
	v_mfma_f32_32x32x16_bf16 v[50:65], v[194:197], v[174:177], v[50:65]
	ds_read_b128 v[226:229], v178 offset:9312
	v_mfma_f32_32x32x16_bf16 v[34:49], v[198:201], v[174:177], v[34:49]
	ds_read_b128 v[230:233], v178 offset:13920
	s_waitcnt lgkmcnt(6)
	v_mfma_f32_32x32x16_bf16 v[18:33], v[194:197], v[190:193], v[18:33]
	v_mfma_f32_32x32x16_bf16 v[2:17], v[198:201], v[190:193], v[2:17]
	s_waitcnt lgkmcnt(0)
	v_mfma_f32_32x32x16_bf16 v[114:129], v[234:237], v[218:221], v[114:129]
	v_mfma_f32_32x32x16_bf16 v[98:113], v[202:205], v[218:221], v[98:113]
	v_mfma_f32_32x32x16_bf16 v[82:97], v[234:237], v[222:225], v[82:97]
	v_mfma_f32_32x32x16_bf16 v[66:81], v[202:205], v[222:225], v[66:81]
	v_mfma_f32_32x32x16_bf16 v[50:65], v[234:237], v[226:229], v[50:65]
	v_mfma_f32_32x32x16_bf16 v[34:49], v[202:205], v[226:229], v[34:49]
	v_mfma_f32_32x32x16_bf16 v[18:33], v[234:237], v[230:233], v[18:33]
	v_mfma_f32_32x32x16_bf16 v[2:17], v[202:205], v[230:233], v[2:17]
	s_mul_i32 s10, s22, 0x2100
	s_lshl_b32 s20, s23, 1
	s_add_u32 s10, s10, s20
	v_lshrrev_b32_e32 v237, 5, v165
	v_and_b32_e32 v194, 31, v165
	v_mul_u32_u24_e32 v234, 0x2100, v237
	v_lshl_add_u32 v234, v194, 4, v234
	v_add_u32_e32 v234, s10, v234
	s_add_i32 s21, s21, s18
	s_ashr_i32 s4, s21, 31
	s_lshr_b32 s4, s4, 27
	s_add_i32 s4, s21, s4
	s_ashr_i32 s4, s4, 5
	v_readlane_b32 s5, v252, 2
	v_readlane_b32 s8, v252, 6
	s_lshl_b32 s5, s4, s5
	s_add_i32 s17, s17, s8
	v_readlane_b32 s8, v252, 9
	s_add_i32 s5, s5, s19
	s_add_i32 s16, s16, s8
	s_cmp_lt_i32 s5, s36
	s_cselect_b32 s10, 1, 0
	s_cmp_eq_u32 s10, 0
	s_cbranch_scc1 .Lg3_nonext_m2
; DI void gemm_phase(const Params& p, int layer, int mode, int nrows, char* lds_all) {
;     ...
;   for (int i = jb;; i += nj) {
;     const int srl = i / per, rem = i - srl * per;
;     const int sr = xcd + nx * srl;
;     if (sr >= nsr) break;
;     const int tn = rem >> 1, tm = sr * 2 + (rem & 1);
;     const int m0 = tm * 256, n0 = tn * 256;
;     ...
;             const float a0 = fmaxf(v0.x, 0.f), a1 = fmaxf(v0.y, 0.f), a2 = fmaxf(v0.z, 0.f), a3 = fmaxf(v0.w, 0.f);
;             const float a4 = fmaxf(v1.x, 0.f), a5 = fmaxf(v1.y, 0.f), a6 = fmaxf(v1.z, 0.f), a7 = fmaxf(v1.w, 0.f);
;             uint4 o;
;             o.x = pack2(a0 * a0, a1 * a1); o.y = pack2(a2 * a2, a3 * a3); o.z = pack2(a4 * a4, a5 * a5); o.w = pack2(a6 * a6, a7 * a7);
;             *(uint4*)((u16*)(p.ws + O_Z) + (size_t)row * HP + col) = o;
	s_lshl_b32 s11, s5, 9
	s_lshl_b32 s5, s21, 8
	s_and_b32 s5, s5, 0x100
	s_lshl_b32 s24, s4, 12
	s_lshl_b32 s4, s21, 7
	s_or_b32 s22, s5, s11
	s_sub_i32 s4, s4, s24
	s_and_b32 s23, s4, 0xffffff00
	s_mul_i32 s4, s22, 0x900
	v_readlane_b32 s8, v250, 46
	s_mul_hi_i32 s5, s22, 0x900
	s_add_u32 s4, s8, s4
	v_readlane_b32 s8, v250, 47
	s_addc_u32 s5, s8, s5
	s_mul_i32 s8, s23, 0x900
	s_mul_hi_i32 s9, s23, 0x900
	s_add_u32 s8, s14, s8
	s_addc_u32 s9, s15, s9
	s_mov_b64 s[26:27], s[4:5]
	s_mov_b64 s[98:99], s[26:27]
	s_mov_b64 s[100:101], s[8:9]
	v_lshrrev_b32_e32 v239, 3, v165
	v_and_b32_e32 v0, 7, v165
	v_mul_u32_u24_e32 v206, 0x900, v239
	v_lshl_add_u32 v206, v0, 4, v206
	v_add_u32_e32 v207, 0x24000, v206
	v_add_u32_e32 v208, 0x48000, v206
	v_add_u32_e32 v238, 0x6c000, v206
	global_load_dwordx4 v[130:133], v206, s[98:99]
	global_load_dwordx4 v[134:137], v207, s[98:99]
	global_load_dwordx4 v[138:141], v208, s[98:99]
	global_load_dwordx4 v[142:145], v238, s[98:99]
	global_load_dwordx4 v[146:149], v206, s[100:101]
	global_load_dwordx4 v[150:153], v207, s[100:101]
	global_load_dwordx4 v[154:157], v208, s[100:101]
	global_load_dwordx4 v[158:161], v238, s[100:101]
	global_load_dwordx4 v[218:221], v206, s[98:99] offset:128
	global_load_dwordx4 v[222:225], v207, s[98:99] offset:128
	global_load_dwordx4 v[226:229], v208, s[98:99] offset:128
	global_load_dwordx4 v[230:233], v238, s[98:99] offset:128
	global_load_dwordx4 v[166:169], v206, s[100:101] offset:128
	global_load_dwordx4 v[170:173], v207, s[100:101] offset:128
	global_load_dwordx4 v[174:177], v208, s[100:101] offset:128
	global_load_dwordx4 v[190:193], v238, s[100:101] offset:128
	s_add_u32 s98, s98, 0x100
	s_addc_u32 s99, s99, 0
	s_add_u32 s100, s100, 0x100
	s_addc_u32 s101, s101, 0
.Lg3_nonext_m2:
	v_lshrrev_b32_e32 v237, 8, v165
	v_and_b32_e32 v194, 31, v165
	v_lshl_or_b32 v237, v237, 7, v194
	v_mul_u32_u24_e32 v236, 0x208, v237
	v_bfe_u32 v237, v165, 6, 2
	v_bfe_u32 v194, v165, 5, 1
	v_lshlrev_b32_e32 v237, 7, v237
	v_lshl_or_b32 v237, v194, 3, v237
	v_add_u32_e32 v236, v236, v237
	v_max_f32_e32 v114, 0, v114
	v_max_f32_e32 v115, 0, v115
	v_max_f32_e32 v116, 0, v116
	v_max_f32_e32 v117, 0, v117
	v_pk_mul_f32 v[114:115], v[114:115], v[114:115]
	v_pk_mul_f32 v[116:117], v[116:117], v[116:117]
	v_cvt_pk_bf16_f32 v114, v114, v115
	v_cvt_pk_bf16_f32 v115, v116, v117
	v_max_f32_e32 v118, 0, v118
	v_max_f32_e32 v119, 0, v119
	v_max_f32_e32 v120, 0, v120
	v_max_f32_e32 v121, 0, v121
	v_pk_mul_f32 v[118:119], v[118:119], v[118:119]
	v_pk_mul_f32 v[120:121], v[120:121], v[120:121]
	v_cvt_pk_bf16_f32 v118, v118, v119
	v_cvt_pk_bf16_f32 v119, v120, v121
	v_max_f32_e32 v122, 0, v122
	v_max_f32_e32 v123, 0, v123
	v_max_f32_e32 v124, 0, v124
	v_max_f32_e32 v125, 0, v125
	v_pk_mul_f32 v[122:123], v[122:123], v[122:123]
	v_pk_mul_f32 v[124:125], v[124:125], v[124:125]
	v_cvt_pk_bf16_f32 v122, v122, v123
	v_cvt_pk_bf16_f32 v123, v124, v125
	v_max_f32_e32 v126, 0, v126
	v_max_f32_e32 v127, 0, v127
	v_max_f32_e32 v128, 0, v128
	v_max_f32_e32 v129, 0, v129
	v_pk_mul_f32 v[126:127], v[126:127], v[126:127]
	v_pk_mul_f32 v[128:129], v[128:129], v[128:129]
	v_cvt_pk_bf16_f32 v126, v126, v127
	v_cvt_pk_bf16_f32 v127, v128, v129
	s_barrier
	ds_write_b64 v236, v[114:115]
	ds_write_b64 v236, v[118:119] offset:16
	ds_write_b64 v236, v[122:123] offset:32
	ds_write_b64 v236, v[126:127] offset:48
	v_max_f32_e32 v98, 0, v98
	v_max_f32_e32 v99, 0, v99
	v_max_f32_e32 v100, 0, v100
	v_max_f32_e32 v101, 0, v101
	v_pk_mul_f32 v[98:99], v[98:99], v[98:99]
	v_pk_mul_f32 v[100:101], v[100:101], v[100:101]
	v_cvt_pk_bf16_f32 v98, v98, v99
	v_cvt_pk_bf16_f32 v99, v100, v101
	v_max_f32_e32 v102, 0, v102
	v_max_f32_e32 v103, 0, v103
	v_max_f32_e32 v104, 0, v104
	v_max_f32_e32 v105, 0, v105
	v_pk_mul_f32 v[102:103], v[102:103], v[102:103]
	v_pk_mul_f32 v[104:105], v[104:105], v[104:105]
	v_cvt_pk_bf16_f32 v102, v102, v103
	v_cvt_pk_bf16_f32 v103, v104, v105
	v_max_f32_e32 v106, 0, v106
	v_max_f32_e32 v107, 0, v107
	v_max_f32_e32 v108, 0, v108
	v_max_f32_e32 v109, 0, v109
	v_pk_mul_f32 v[106:107], v[106:107], v[106:107]
	v_pk_mul_f32 v[108:109], v[108:109], v[108:109]
	v_cvt_pk_bf16_f32 v106, v106, v107
	v_cvt_pk_bf16_f32 v107, v108, v109
	v_max_f32_e32 v110, 0, v110
	v_max_f32_e32 v111, 0, v111
	v_max_f32_e32 v112, 0, v112
	v_max_f32_e32 v113, 0, v113
	v_pk_mul_f32 v[110:111], v[110:111], v[110:111]
	v_pk_mul_f32 v[112:113], v[112:113], v[112:113]
	v_cvt_pk_bf16_f32 v110, v110, v111
	v_cvt_pk_bf16_f32 v111, v112, v113
	ds_write_b64 v236, v[98:99] offset:64
	ds_write_b64 v236, v[102:103] offset:80
	ds_write_b64 v236, v[106:107] offset:96
	ds_write_b64 v236, v[110:111] offset:112
	v_max_f32_e32 v82, 0, v82
	v_max_f32_e32 v83, 0, v83
	v_max_f32_e32 v84, 0, v84
	v_max_f32_e32 v85, 0, v85
	v_pk_mul_f32 v[82:83], v[82:83], v[82:83]
	v_pk_mul_f32 v[84:85], v[84:85], v[84:85]
	v_cvt_pk_bf16_f32 v82, v82, v83
	v_cvt_pk_bf16_f32 v83, v84, v85
	v_max_f32_e32 v86, 0, v86
	v_max_f32_e32 v87, 0, v87
	v_max_f32_e32 v88, 0, v88
	v_max_f32_e32 v89, 0, v89
	v_pk_mul_f32 v[86:87], v[86:87], v[86:87]
	v_pk_mul_f32 v[88:89], v[88:89], v[88:89]
	v_cvt_pk_bf16_f32 v86, v86, v87
	v_cvt_pk_bf16_f32 v87, v88, v89
	v_max_f32_e32 v90, 0, v90
	v_max_f32_e32 v91, 0, v91
	v_max_f32_e32 v92, 0, v92
	v_max_f32_e32 v93, 0, v93
	v_pk_mul_f32 v[90:91], v[90:91], v[90:91]
	v_pk_mul_f32 v[92:93], v[92:93], v[92:93]
	v_cvt_pk_bf16_f32 v90, v90, v91
	v_cvt_pk_bf16_f32 v91, v92, v93
	v_max_f32_e32 v94, 0, v94
	v_max_f32_e32 v95, 0, v95
	v_max_f32_e32 v96, 0, v96
	v_max_f32_e32 v97, 0, v97
	v_pk_mul_f32 v[94:95], v[94:95], v[94:95]
	v_pk_mul_f32 v[96:97], v[96:97], v[96:97]
; DI void gemm_phase(const Params& p, int layer, int mode, int nrows, char* lds_all) {
;     ...
;             const float a0 = fmaxf(v0.x, 0.f), a1 = fmaxf(v0.y, 0.f), a2 = fmaxf(v0.z, 0.f), a3 = fmaxf(v0.w, 0.f);
;             const float a4 = fmaxf(v1.x, 0.f), a5 = fmaxf(v1.y, 0.f), a6 = fmaxf(v1.z, 0.f), a7 = fmaxf(v1.w, 0.f);
;             uint4 o;
;             o.x = pack2(a0 * a0, a1 * a1); o.y = pack2(a2 * a2, a3 * a3); o.z = pack2(a4 * a4, a5 * a5); o.w = pack2(a6 * a6, a7 * a7);
;             *(uint4*)((u16*)(p.ws + O_Z) + (size_t)row * HP + col) = o;
	v_cvt_pk_bf16_f32 v94, v94, v95
	v_cvt_pk_bf16_f32 v95, v96, v97
	ds_write_b64 v236, v[82:83] offset:16640
	ds_write_b64 v236, v[86:87] offset:16656
	ds_write_b64 v236, v[90:91] offset:16672
	ds_write_b64 v236, v[94:95] offset:16688
	v_max_f32_e32 v66, 0, v66
	v_max_f32_e32 v67, 0, v67
	v_max_f32_e32 v68, 0, v68
	v_max_f32_e32 v69, 0, v69
	v_pk_mul_f32 v[66:67], v[66:67], v[66:67]
	v_pk_mul_f32 v[68:69], v[68:69], v[68:69]
	v_cvt_pk_bf16_f32 v66, v66, v67
	v_cvt_pk_bf16_f32 v67, v68, v69
	v_max_f32_e32 v70, 0, v70
	v_max_f32_e32 v71, 0, v71
	v_max_f32_e32 v72, 0, v72
	v_max_f32_e32 v73, 0, v73
	v_pk_mul_f32 v[70:71], v[70:71], v[70:71]
	v_pk_mul_f32 v[72:73], v[72:73], v[72:73]
	v_cvt_pk_bf16_f32 v70, v70, v71
	v_cvt_pk_bf16_f32 v71, v72, v73
	v_max_f32_e32 v74, 0, v74
	v_max_f32_e32 v75, 0, v75
	v_max_f32_e32 v76, 0, v76
	v_max_f32_e32 v77, 0, v77
	v_pk_mul_f32 v[74:75], v[74:75], v[74:75]
	v_pk_mul_f32 v[76:77], v[76:77], v[76:77]
	v_cvt_pk_bf16_f32 v74, v74, v75
	v_cvt_pk_bf16_f32 v75, v76, v77
	v_max_f32_e32 v78, 0, v78
	v_max_f32_e32 v79, 0, v79
	v_max_f32_e32 v80, 0, v80
	v_max_f32_e32 v81, 0, v81
	v_pk_mul_f32 v[78:79], v[78:79], v[78:79]
	v_pk_mul_f32 v[80:81], v[80:81], v[80:81]
	v_cvt_pk_bf16_f32 v78, v78, v79
	v_cvt_pk_bf16_f32 v79, v80, v81
	ds_write_b64 v236, v[66:67] offset:16704
	ds_write_b64 v236, v[70:71] offset:16720
	ds_write_b64 v236, v[74:75] offset:16736
	ds_write_b64 v236, v[78:79] offset:16752
	v_max_f32_e32 v50, 0, v50
	v_max_f32_e32 v51, 0, v51
	v_max_f32_e32 v52, 0, v52
	v_max_f32_e32 v53, 0, v53
	v_pk_mul_f32 v[50:51], v[50:51], v[50:51]
	v_pk_mul_f32 v[52:53], v[52:53], v[52:53]
	v_cvt_pk_bf16_f32 v50, v50, v51
	v_cvt_pk_bf16_f32 v51, v52, v53
	v_max_f32_e32 v54, 0, v54
	v_max_f32_e32 v55, 0, v55
	v_max_f32_e32 v56, 0, v56
	v_max_f32_e32 v57, 0, v57
	v_pk_mul_f32 v[54:55], v[54:55], v[54:55]
	v_pk_mul_f32 v[56:57], v[56:57], v[56:57]
	v_cvt_pk_bf16_f32 v54, v54, v55
	v_cvt_pk_bf16_f32 v55, v56, v57
	v_max_f32_e32 v58, 0, v58
	v_max_f32_e32 v59, 0, v59
	v_max_f32_e32 v60, 0, v60
	v_max_f32_e32 v61, 0, v61
	v_pk_mul_f32 v[58:59], v[58:59], v[58:59]
	v_pk_mul_f32 v[60:61], v[60:61], v[60:61]
	v_cvt_pk_bf16_f32 v58, v58, v59
	v_cvt_pk_bf16_f32 v59, v60, v61
	v_max_f32_e32 v62, 0, v62
	v_max_f32_e32 v63, 0, v63
	v_max_f32_e32 v64, 0, v64
	v_max_f32_e32 v65, 0, v65
	v_pk_mul_f32 v[62:63], v[62:63], v[62:63]
	v_pk_mul_f32 v[64:65], v[64:65], v[64:65]
	v_cvt_pk_bf16_f32 v62, v62, v63
	v_cvt_pk_bf16_f32 v63, v64, v65
	ds_write_b64 v236, v[50:51] offset:33280
	ds_write_b64 v236, v[54:55] offset:33296
	ds_write_b64 v236, v[58:59] offset:33312
	ds_write_b64 v236, v[62:63] offset:33328
	v_max_f32_e32 v34, 0, v34
	v_max_f32_e32 v35, 0, v35
	v_max_f32_e32 v36, 0, v36
	v_max_f32_e32 v37, 0, v37
	v_pk_mul_f32 v[34:35], v[34:35], v[34:35]
	v_pk_mul_f32 v[36:37], v[36:37], v[36:37]
	v_cvt_pk_bf16_f32 v34, v34, v35
	v_cvt_pk_bf16_f32 v35, v36, v37
	v_max_f32_e32 v38, 0, v38
	v_max_f32_e32 v39, 0, v39
	v_max_f32_e32 v40, 0, v40
	v_max_f32_e32 v41, 0, v41
	v_pk_mul_f32 v[38:39], v[38:39], v[38:39]
	v_pk_mul_f32 v[40:41], v[40:41], v[40:41]
	v_cvt_pk_bf16_f32 v38, v38, v39
	v_cvt_pk_bf16_f32 v39, v40, v41
	v_max_f32_e32 v42, 0, v42
	v_max_f32_e32 v43, 0, v43
	v_max_f32_e32 v44, 0, v44
	v_max_f32_e32 v45, 0, v45
	v_pk_mul_f32 v[42:43], v[42:43], v[42:43]
	v_pk_mul_f32 v[44:45], v[44:45], v[44:45]
	v_cvt_pk_bf16_f32 v42, v42, v43
	v_cvt_pk_bf16_f32 v43, v44, v45
	v_max_f32_e32 v46, 0, v46
	v_max_f32_e32 v47, 0, v47
	v_max_f32_e32 v48, 0, v48
	v_max_f32_e32 v49, 0, v49
	v_pk_mul_f32 v[46:47], v[46:47], v[46:47]
	v_pk_mul_f32 v[48:49], v[48:49], v[48:49]
	v_cvt_pk_bf16_f32 v46, v46, v47
	v_cvt_pk_bf16_f32 v47, v48, v49
	ds_write_b64 v236, v[34:35] offset:33344
	ds_write_b64 v236, v[38:39] offset:33360
	ds_write_b64 v236, v[42:43] offset:33376
	ds_write_b64 v236, v[46:47] offset:33392
	v_max_f32_e32 v18, 0, v18
	v_max_f32_e32 v19, 0, v19
	v_max_f32_e32 v20, 0, v20
	v_max_f32_e32 v21, 0, v21
	v_pk_mul_f32 v[18:19], v[18:19], v[18:19]
	v_pk_mul_f32 v[20:21], v[20:21], v[20:21]
	v_cvt_pk_bf16_f32 v18, v18, v19
	v_cvt_pk_bf16_f32 v19, v20, v21
	v_max_f32_e32 v22, 0, v22
	v_max_f32_e32 v23, 0, v23
	v_max_f32_e32 v24, 0, v24
	v_max_f32_e32 v25, 0, v25
	v_pk_mul_f32 v[22:23], v[22:23], v[22:23]
	v_pk_mul_f32 v[24:25], v[24:25], v[24:25]
	v_cvt_pk_bf16_f32 v22, v22, v23
	v_cvt_pk_bf16_f32 v23, v24, v25
	v_max_f32_e32 v26, 0, v26
	v_max_f32_e32 v27, 0, v27
	v_max_f32_e32 v28, 0, v28
	v_max_f32_e32 v29, 0, v29
	v_pk_mul_f32 v[26:27], v[26:27], v[26:27]
	v_pk_mul_f32 v[28:29], v[28:29], v[28:29]
	v_cvt_pk_bf16_f32 v26, v26, v27
	v_cvt_pk_bf16_f32 v27, v28, v29
	v_max_f32_e32 v30, 0, v30
	v_max_f32_e32 v31, 0, v31
	v_max_f32_e32 v32, 0, v32
	v_max_f32_e32 v33, 0, v33
	v_pk_mul_f32 v[30:31], v[30:31], v[30:31]
	v_pk_mul_f32 v[32:33], v[32:33], v[32:33]
	v_cvt_pk_bf16_f32 v30, v30, v31
	v_cvt_pk_bf16_f32 v31, v32, v33
	ds_write_b64 v236, v[18:19] offset:49920
	ds_write_b64 v236, v[22:23] offset:49936
	ds_write_b64 v236, v[26:27] offset:49952
	ds_write_b64 v236, v[30:31] offset:49968
	v_max_f32_e32 v2, 0, v2
	v_max_f32_e32 v3, 0, v3
	v_max_f32_e32 v4, 0, v4
	v_max_f32_e32 v5, 0, v5
	v_pk_mul_f32 v[2:3], v[2:3], v[2:3]
	v_pk_mul_f32 v[4:5], v[4:5], v[4:5]
	v_cvt_pk_bf16_f32 v2, v2, v3
	v_cvt_pk_bf16_f32 v3, v4, v5
	v_max_f32_e32 v6, 0, v6
	v_max_f32_e32 v7, 0, v7
	v_max_f32_e32 v8, 0, v8
	v_max_f32_e32 v9, 0, v9
	v_pk_mul_f32 v[6:7], v[6:7], v[6:7]
	v_pk_mul_f32 v[8:9], v[8:9], v[8:9]
	v_cvt_pk_bf16_f32 v6, v6, v7
	v_cvt_pk_bf16_f32 v7, v8, v9
	v_max_f32_e32 v10, 0, v10
	v_max_f32_e32 v11, 0, v11
	v_max_f32_e32 v12, 0, v12
	v_max_f32_e32 v13, 0, v13
	v_pk_mul_f32 v[10:11], v[10:11], v[10:11]
	v_pk_mul_f32 v[12:13], v[12:13], v[12:13]
	v_cvt_pk_bf16_f32 v10, v10, v11
	v_cvt_pk_bf16_f32 v11, v12, v13
	v_max_f32_e32 v14, 0, v14
	v_max_f32_e32 v15, 0, v15
	v_max_f32_e32 v16, 0, v16
	v_max_f32_e32 v17, 0, v17
	v_pk_mul_f32 v[14:15], v[14:15], v[14:15]
	v_pk_mul_f32 v[16:17], v[16:17], v[16:17]
	v_cvt_pk_bf16_f32 v14, v14, v15
	v_cvt_pk_bf16_f32 v15, v16, v17
	ds_write_b64 v236, v[2:3] offset:49984
	ds_write_b64 v236, v[6:7] offset:50000
	ds_write_b64 v236, v[10:11] offset:50016
	ds_write_b64 v236, v[14:15] offset:50032
	s_waitcnt lgkmcnt(0)
	s_barrier
; DI void gemm_phase(const Params& p, int layer, int mode, int nrows, char* lds_all) {
;     ...
;         for (int idx = tid; idx < 128 * 32; idx += 512) {
;           const int rr = idx >> 5, c8 = (idx & 31) * 8;
;           const int row = m0 + half * 128 + rr, col = n0 + c8;
;           const float4 v0 = *(const float4*)(Cs + rr * CSW + c8), v1 = *(const float4*)(Cs + rr * CSW + c8 + 4);
;           if (mode == 0) {
;             uint4 o;
;             o.x = pack2(v0.x, v0.y); o.y = pack2(v0.z, v0.w); o.z = pack2(v1.x, v1.y); o.w = pack2(v1.z, v1.w);
;             *(uint4*)((u16*)(p.ws + O_Z) + (size_t)row * ZW + col) = o;
;             if (n0 == C_BAB && c8 < 16) {
;               *(float4*)((float*)(p.ws + O_GRAW) + (size_t)row * 16 + c8) = v0;
;               *(float4*)((float*)(p.ws + O_GRAW) + (size_t)row * 16 + c8 + 4) = v1;
;             }
;           } else {
;             const float a0 = fmaxf(v0.x, 0.f), a1 = fmaxf(v0.y, 0.f), a2 = fmaxf(v0.z, 0.f), a3 = fmaxf(v0.w, 0.f);
;             const float a4 = fmaxf(v1.x, 0.f), a5 = fmaxf(v1.y, 0.f), a6 = fmaxf(v1.z, 0.f), a7 = fmaxf(v1.w, 0.f);
;             uint4 o;
;             o.x = pack2(a0 * a0, a1 * a1); o.y = pack2(a2 * a2, a3 * a3); o.z = pack2(a4 * a4, a5 * a5); o.w = pack2(a6 * a6, a7 * a7);
;             *(uint4*)((u16*)(p.ws + O_Z) + (size_t)row * HP + col) = o;
;           }
;         }
	v_lshrrev_b32_e32 v237, 5, v165
	v_and_b32_e32 v194, 31, v165
	v_mul_u32_u24_e32 v235, 0x208, v237
	v_lshl_add_u32 v235, v194, 4, v235
	ds_read2_b64 v[2:5], v235 offset1:1
	v_add_u32_e32 v235, 0x2080, v235
	ds_read2_b64 v[6:9], v235 offset1:1
	v_add_u32_e32 v235, 0x2080, v235
	ds_read2_b64 v[10:13], v235 offset1:1
	v_add_u32_e32 v235, 0x2080, v235
	ds_read2_b64 v[14:17], v235 offset1:1
	v_add_u32_e32 v235, 0x2080, v235
	ds_read2_b64 v[18:21], v235 offset1:1
	v_add_u32_e32 v235, 0x2080, v235
	ds_read2_b64 v[22:25], v235 offset1:1
	v_add_u32_e32 v235, 0x2080, v235
	ds_read2_b64 v[26:29], v235 offset1:1
	v_add_u32_e32 v235, 0x2080, v235
	ds_read2_b64 v[30:33], v235 offset1:1
	v_add_u32_e32 v235, 0x2080, v235
	ds_read2_b64 v[34:37], v235 offset1:1
	v_add_u32_e32 v235, 0x2080, v235
	ds_read2_b64 v[38:41], v235 offset1:1
	v_add_u32_e32 v235, 0x2080, v235
	ds_read2_b64 v[42:45], v235 offset1:1
	v_add_u32_e32 v235, 0x2080, v235
	ds_read2_b64 v[46:49], v235 offset1:1
	v_add_u32_e32 v235, 0x2080, v235
	ds_read2_b64 v[50:53], v235 offset1:1
	v_add_u32_e32 v235, 0x2080, v235
	ds_read2_b64 v[54:57], v235 offset1:1
	v_add_u32_e32 v235, 0x2080, v235
	ds_read2_b64 v[58:61], v235 offset1:1
	v_add_u32_e32 v235, 0x2080, v235
	ds_read2_b64 v[62:65], v235 offset1:1
	s_waitcnt lgkmcnt(15)
	global_store_dwordx4 v234, v[2:5], s[50:51]
	v_add_u32_e32 v234, 0x21000, v234
	s_waitcnt lgkmcnt(14)
	global_store_dwordx4 v234, v[6:9], s[50:51]
	v_add_u32_e32 v234, 0x21000, v234
	s_waitcnt lgkmcnt(13)
	global_store_dwordx4 v234, v[10:13], s[50:51]
	v_add_u32_e32 v234, 0x21000, v234
	s_waitcnt lgkmcnt(12)
	global_store_dwordx4 v234, v[14:17], s[50:51]
	v_add_u32_e32 v234, 0x21000, v234
	s_waitcnt lgkmcnt(11)
	global_store_dwordx4 v234, v[18:21], s[50:51]
	v_add_u32_e32 v234, 0x21000, v234
	s_waitcnt lgkmcnt(10)
	global_store_dwordx4 v234, v[22:25], s[50:51]
	v_add_u32_e32 v234, 0x21000, v234
	s_waitcnt lgkmcnt(9)
	global_store_dwordx4 v234, v[26:29], s[50:51]
	v_add_u32_e32 v234, 0x21000, v234
	s_waitcnt lgkmcnt(8)
	global_store_dwordx4 v234, v[30:33], s[50:51]
	v_add_u32_e32 v234, 0x21000, v234
	s_waitcnt lgkmcnt(7)
	global_store_dwordx4 v234, v[34:37], s[50:51]
	v_add_u32_e32 v234, 0x21000, v234
	s_waitcnt lgkmcnt(6)
	global_store_dwordx4 v234, v[38:41], s[50:51]
	v_add_u32_e32 v234, 0x21000, v234
	s_waitcnt lgkmcnt(5)
	global_store_dwordx4 v234, v[42:45], s[50:51]
	v_add_u32_e32 v234, 0x21000, v234
	s_waitcnt lgkmcnt(4)
	global_store_dwordx4 v234, v[46:49], s[50:51]
	v_add_u32_e32 v234, 0x21000, v234
	s_waitcnt lgkmcnt(3)
	global_store_dwordx4 v234, v[50:53], s[50:51]
	v_add_u32_e32 v234, 0x21000, v234
	s_waitcnt lgkmcnt(2)
	global_store_dwordx4 v234, v[54:57], s[50:51]
	v_add_u32_e32 v234, 0x21000, v234
	s_waitcnt lgkmcnt(1)
	global_store_dwordx4 v234, v[58:61], s[50:51]
	v_add_u32_e32 v234, 0x21000, v234
	s_waitcnt lgkmcnt(0)
	global_store_dwordx4 v234, v[62:65], s[50:51]
	s_cmp_lg_u32 s10, 0
	s_cbranch_scc1 .Lg3_start_m2
	v_mov_b32_e32 v190, 0x10c20
	v_mov_b32_e32 v191, 0x11040
	v_mov_b32_e32 v192, 0x11460
	v_mov_b32_e32 v193, 0x12900
	v_mov_b32_e32 v194, 0x12d20
	v_mov_b32_e32 v195, 0x13140
	v_mov_b32_e32 v196, 0x13560
	v_mov_b32_e32 v197, 0x14a00
	v_mov_b32_e32 v198, 0x14e20
	v_mov_b32_e32 v199, 0x15240
	v_mov_b32_e32 v200, 0x15660
	v_mov_b32_e32 v201, 0x16b00
	v_mov_b32_e32 v202, 0x16f20
	v_mov_b32_e32 v203, 0x17340
	v_mov_b32_e32 v204, 0x17760
	v_mov_b32_e32 v205, 0x18c00
	v_mov_b32_e32 v206, 0x19020
	v_mov_b32_e32 v207, 0x19440
	v_mov_b32_e32 v208, 0x10800
	s_branch .LBB0_842
